# IDX QK-norm loop unrolled and software-pipelined: gain loads and all 20 row loads issued first, math sequence unchanged (bit-identical)
# speedup vs baseline: 1.0043x; 1.0043x over previous
; __device__ __forceinline__ void idx_unit(bf16* QB, float* SC, int* SEL, const float* qg, const float* kg, int b, int tp, LAS unsigned char* wl, int lane, bool do_norm) {
;     ...
;     if (!do_norm) return;
;     const int lg = lane >> 4, li = lane & 15;
; #pragma unroll 1
;     for (int a = 0; a < 4; ++a)
; #pragma unroll 1
;         for (int p = 0; p < 5; ++p) {
;             const int col = (p < 4) ? (CQ + (4 * p + lg) * 128) : (CK + lg * 128);
;             bf16* ptr = QB + (row + a) * NBP + col + 8 * li;
;             const u32x4 w = *(const u32x4*)ptr;
;             float v[8] = {bflo(w.x), bfhi(w.x), bflo(w.y), bfhi(w.y), bflo(w.z), bfhi(w.z), bflo(w.w), bfhi(w.w)};
;             float s = 0.f;
; #pragma unroll
;             for (int e = 0; e < 8; ++e) s += v[e] * v[e];
;             s += __shfl_xor(s, 1); s += __shfl_xor(s, 2); s += __shfl_xor(s, 4); s += __shfl_xor(s, 8);
;             const float rstd = (1.0f / sqrtf(s * (1.f / 128.f) + RMS_EPS)) * ((p < 4) ? C2 : 1.f);
;             const float* gp = ((p < 4) ? qg : kg) + 8 * li;
;             const f32x4 g0 = *(const f32x4*)gp, g1 = *(const f32x4*)(gp + 4);
.LBB0_561:
	v_readlane_b32 s66, v253, 47
	v_readlane_b32 s84, v253, 49
	v_readlane_b32 s58, v253, 44
	v_readlane_b32 s67, v253, 48
	v_readlane_b32 s85, v253, 50
	v_readlane_b32 s88, v253, 59
	s_mov_b32 s3, 0
	v_readlane_b32 s59, v253, 45
	v_readlane_b32 s64, v253, 46
	v_readlane_b32 s67, v253, 55
	v_readlane_b32 s85, v253, 56
	v_readlane_b32 s86, v253, 57
	v_readlane_b32 s87, v253, 58
	v_readlane_b32 s89, v253, 60
	s_movk_i32 s92, 0x3000
	s_movk_i32 s93, 0x5a
	s_mov_b32 s94, 0xff800000
	v_readlane_b32 s49, v254, 6
	v_readlane_b32 s11, v250, 33
	s_add_u32 s0, s80, s76
	s_addc_u32 s1, s81, s77
	global_load_dwordx4 v[222:225], v105, s[0:1] offset:16
	global_load_dwordx4 v[218:221], v105, s[0:1]
	s_add_u32 s0, s82, s76
	s_addc_u32 s1, s83, s77
	global_load_dwordx4 v[230:233], v105, s[0:1] offset:16
	global_load_dwordx4 v[226:229], v105, s[0:1]
	s_add_u32 s0, s2, 0
	s_addc_u32 s1, s79, 0
	s_mul_i32 s4, s1, 0x2200
	v_mad_u64_u32 v[0:1], s[0:1], s0, v212, v[118:119]
	v_add_u32_e32 v1, s4, v1
	v_mov_b32_e32 v2, v216
	v_ashrrev_i32_e32 v3, 31, v2
	v_lshl_add_u64 v[14:15], v[2:3], 1, v[0:1]
	global_load_dwordx4 v[16:19], v[14:15], off
	v_add_u32_e32 v2, 0x200, v216
	v_ashrrev_i32_e32 v3, 31, v2
	v_lshl_add_u64 v[14:15], v[2:3], 1, v[0:1]
	global_load_dwordx4 v[20:23], v[14:15], off
	v_add_u32_e32 v2, 0x400, v216
	v_ashrrev_i32_e32 v3, 31, v2
	v_lshl_add_u64 v[14:15], v[2:3], 1, v[0:1]
	global_load_dwordx4 v[24:27], v[14:15], off
	v_add_u32_e32 v2, 0x600, v216
	v_ashrrev_i32_e32 v3, 31, v2
	v_lshl_add_u64 v[14:15], v[2:3], 1, v[0:1]
	global_load_dwordx4 v[28:31], v[14:15], off
	v_add_u32_e32 v2, 0x800, v216
	v_ashrrev_i32_e32 v3, 31, v2
	v_lshl_add_u64 v[14:15], v[2:3], 1, v[0:1]
	global_load_dwordx4 v[32:35], v[14:15], off
	s_add_u32 s0, s2, 1
	s_addc_u32 s1, s79, 0
	s_mul_i32 s4, s1, 0x2200
	v_mad_u64_u32 v[0:1], s[0:1], s0, v212, v[118:119]
	v_add_u32_e32 v1, s4, v1
	v_mov_b32_e32 v2, v216
	v_ashrrev_i32_e32 v3, 31, v2
	v_lshl_add_u64 v[14:15], v[2:3], 1, v[0:1]
	global_load_dwordx4 v[36:39], v[14:15], off
	v_add_u32_e32 v2, 0x200, v216
	v_ashrrev_i32_e32 v3, 31, v2
	v_lshl_add_u64 v[14:15], v[2:3], 1, v[0:1]
	global_load_dwordx4 v[40:43], v[14:15], off
	v_add_u32_e32 v2, 0x400, v216
	v_ashrrev_i32_e32 v3, 31, v2
	v_lshl_add_u64 v[14:15], v[2:3], 1, v[0:1]
	global_load_dwordx4 v[44:47], v[14:15], off
	v_add_u32_e32 v2, 0x600, v216
	v_ashrrev_i32_e32 v3, 31, v2
	v_lshl_add_u64 v[14:15], v[2:3], 1, v[0:1]
	global_load_dwordx4 v[48:51], v[14:15], off
	v_add_u32_e32 v2, 0x800, v216
	v_ashrrev_i32_e32 v3, 31, v2
	v_lshl_add_u64 v[14:15], v[2:3], 1, v[0:1]
	global_load_dwordx4 v[52:55], v[14:15], off
	s_add_u32 s0, s2, 2
	s_addc_u32 s1, s79, 0
	s_mul_i32 s4, s1, 0x2200
	v_mad_u64_u32 v[0:1], s[0:1], s0, v212, v[118:119]
	v_add_u32_e32 v1, s4, v1
	v_mov_b32_e32 v2, v216
	v_ashrrev_i32_e32 v3, 31, v2
	v_lshl_add_u64 v[14:15], v[2:3], 1, v[0:1]
	global_load_dwordx4 v[56:59], v[14:15], off
	v_add_u32_e32 v2, 0x200, v216
	v_ashrrev_i32_e32 v3, 31, v2
	v_lshl_add_u64 v[14:15], v[2:3], 1, v[0:1]
	global_load_dwordx4 v[60:63], v[14:15], off
	v_add_u32_e32 v2, 0x400, v216
	v_ashrrev_i32_e32 v3, 31, v2
	v_lshl_add_u64 v[14:15], v[2:3], 1, v[0:1]
	global_load_dwordx4 v[64:67], v[14:15], off
	v_add_u32_e32 v2, 0x600, v216
	v_ashrrev_i32_e32 v3, 31, v2
	v_lshl_add_u64 v[14:15], v[2:3], 1, v[0:1]
	global_load_dwordx4 v[68:71], v[14:15], off
	v_add_u32_e32 v2, 0x800, v216
	v_ashrrev_i32_e32 v3, 31, v2
	v_lshl_add_u64 v[14:15], v[2:3], 1, v[0:1]
	global_load_dwordx4 v[72:75], v[14:15], off
	s_add_u32 s0, s2, 3
	s_addc_u32 s1, s79, 0
	s_mul_i32 s4, s1, 0x2200
	v_mad_u64_u32 v[0:1], s[0:1], s0, v212, v[118:119]
	v_add_u32_e32 v1, s4, v1
	v_mov_b32_e32 v2, v216
	v_ashrrev_i32_e32 v3, 31, v2
	v_lshl_add_u64 v[14:15], v[2:3], 1, v[0:1]
	global_load_dwordx4 v[76:79], v[14:15], off
	v_add_u32_e32 v2, 0x200, v216
	v_ashrrev_i32_e32 v3, 31, v2
	v_lshl_add_u64 v[14:15], v[2:3], 1, v[0:1]
	global_load_dwordx4 v[80:83], v[14:15], off
	v_add_u32_e32 v2, 0x400, v216
	v_ashrrev_i32_e32 v3, 31, v2
	v_lshl_add_u64 v[14:15], v[2:3], 1, v[0:1]
	global_load_dwordx4 v[84:87], v[14:15], off
	v_add_u32_e32 v2, 0x600, v216
	v_ashrrev_i32_e32 v3, 31, v2
	v_lshl_add_u64 v[14:15], v[2:3], 1, v[0:1]
	global_load_dwordx4 v[88:91], v[14:15], off
	v_add_u32_e32 v2, 0x800, v216
	v_ashrrev_i32_e32 v3, 31, v2
	v_lshl_add_u64 v[14:15], v[2:3], 1, v[0:1]
	global_load_dwordx4 v[92:95], v[14:15], off
	s_add_u32 s0, s2, 0
	s_addc_u32 s1, s79, 0
	s_mul_i32 s4, s1, 0x2200
	v_mad_u64_u32 v[0:1], s[0:1], s0, v212, v[118:119]
	v_add_u32_e32 v1, s4, v1
	s_waitcnt vmcnt(19)
	v_mov_b32_e32 v217, v211
	v_lshlrev_b32_e32 v234, 16, v16
	v_and_b32_e32 v16, 0xffff0000, v16
	v_mul_f32_e32 v238, v16, v16
	v_lshlrev_b32_e32 v235, 16, v17
	v_fmac_f32_e32 v238, v234, v234
	v_and_b32_e32 v17, 0xffff0000, v17
	v_fmac_f32_e32 v238, v235, v235
	v_lshlrev_b32_e32 v236, 16, v18
	v_fmac_f32_e32 v238, v17, v17
	v_and_b32_e32 v18, 0xffff0000, v18
	v_fmac_f32_e32 v238, v236, v236
	v_lshlrev_b32_e32 v237, 16, v19
	v_fmac_f32_e32 v238, v18, v18
	v_and_b32_e32 v19, 0xffff0000, v19
	v_fmac_f32_e32 v238, v237, v237
	v_fmac_f32_e32 v238, v19, v19
	ds_bpermute_b32 v239, v204, v238
	s_waitcnt lgkmcnt(0)
	v_add_f32_e32 v238, v238, v239
	ds_bpermute_b32 v239, v205, v238
	s_waitcnt lgkmcnt(0)
	v_add_f32_e32 v238, v238, v239
	ds_bpermute_b32 v239, v214, v238
	s_waitcnt lgkmcnt(0)
	v_add_f32_e32 v238, v238, v239
	ds_bpermute_b32 v239, v215, v238
	s_waitcnt lgkmcnt(0)
; __device__ __forceinline__ unsigned pk2(float lo, float hi) { return pg8::cvt_pk_bf16(lo, hi); }
; __device__ __forceinline__ void idx_unit(bf16* QB, float* SC, int* SEL, const float* qg, const float* kg, int b, int tp, LAS unsigned char* wl, int lane, bool do_norm) {
;     ...
;             const int col = (p < 4) ? (CQ + (4 * p + lg) * 128) : (CK + lg * 128);
;             bf16* ptr = QB + (row + a) * NBP + col + 8 * li;
;             const u32x4 w = *(const u32x4*)ptr;
;             float v[8] = {bflo(w.x), bfhi(w.x), bflo(w.y), bfhi(w.y), bflo(w.z), bfhi(w.z), bflo(w.w), bfhi(w.w)};
;             float s = 0.f;
; #pragma unroll
;             for (int e = 0; e < 8; ++e) s += v[e] * v[e];
;             s += __shfl_xor(s, 1); s += __shfl_xor(s, 2); s += __shfl_xor(s, 4); s += __shfl_xor(s, 8);
;             const float rstd = (1.0f / sqrtf(s * (1.f / 128.f) + RMS_EPS)) * ((p < 4) ? C2 : 1.f);
;             const float* gp = ((p < 4) ? qg : kg) + 8 * li;
;             const f32x4 g0 = *(const f32x4*)gp, g1 = *(const f32x4*)(gp + 4);
;             u32x4 o; o.x = pk2(v[0] * rstd * g0.x, v[1] * rstd * g0.y); o.y = pk2(v[2] * rstd * g0.z, v[3] * rstd * g0.w);
;             o.z = pk2(v[4] * rstd * g1.x, v[5] * rstd * g1.y); o.w = pk2(v[6] * rstd * g1.z, v[7] * rstd * g1.w);
;             *(u32x4*)ptr = o;
	v_add_f32_e32 v238, v238, v239
	v_fmamk_f32 v238, v238, 0x3c000000, v208
	v_mul_f32_e32 v239, 0x4f800000, v238
	v_cmp_gt_f32_e32 vcc, s33, v238
	s_nop 1
	v_cndmask_b32_e32 v238, v238, v239, vcc
	v_sqrt_f32_e32 v239, v238
	s_nop 0
	v_add_u32_e32 v240, -1, v239
	v_add_u32_e32 v241, 1, v239
	v_fma_f32 v242, -v240, v239, v238
	v_fma_f32 v243, -v241, v239, v238
	v_cmp_ge_f32_e64 s[0:1], 0, v242
	s_nop 1
	v_cndmask_b32_e64 v239, v239, v240, s[0:1]
	v_cmp_lt_f32_e64 s[0:1], 0, v243
	s_nop 1
	v_cndmask_b32_e64 v239, v239, v241, s[0:1]
	v_mul_f32_e32 v240, 0x37800000, v239
	v_cndmask_b32_e32 v239, v239, v240, vcc
	v_cmp_class_f32_e32 vcc, v238, v209
	s_nop 1
	v_cndmask_b32_e32 v238, v239, v238, vcc
	v_div_scale_f32 v239, s[0:1], v238, v238, 1.0
	v_rcp_f32_e32 v241, v239
	v_div_scale_f32 v240, vcc, 1.0, v238, 1.0
	v_fma_f32 v242, -v239, v241, 1.0
	v_fmac_f32_e32 v241, v242, v241
	v_mul_f32_e32 v242, v240, v241
	v_fma_f32 v243, -v239, v242, v240
	v_fmac_f32_e32 v242, v243, v241
	v_fma_f32 v239, -v239, v242, v240
	v_div_fmas_f32 v239, v239, v241, v242
	v_div_fixup_f32 v238, v239, v238, 1.0
	v_mul_f32_e32 v217, v217, v238
	v_mul_f32_e32 v16, v217, v16
	v_mul_f32_e32 v17, v217, v17
	v_mul_f32_e32 v18, v217, v18
	v_mul_f32_e32 v19, v217, v19
	v_mul_f32_e32 v234, v217, v234
	v_mul_f32_e32 v235, v217, v235
	v_mul_f32_e32 v236, v217, v236
	v_mul_f32_e32 v237, v217, v237
	v_mul_f32_e32 v16, v219, v16
	v_mul_f32_e32 v17, v221, v17
	v_mul_f32_e32 v18, v223, v18
	v_mul_f32_e32 v19, v225, v19
	v_mul_f32_e32 v244, v218, v234
	v_mul_f32_e32 v245, v220, v235
	v_mul_f32_e32 v246, v222, v236
	v_mul_f32_e32 v247, v224, v237
	v_cvt_pk_bf16_f32 v16, v244, v16
	v_cvt_pk_bf16_f32 v17, v245, v17
	v_cvt_pk_bf16_f32 v18, v246, v18
	v_cvt_pk_bf16_f32 v19, v247, v19
	v_mov_b32_e32 v2, v216
	v_ashrrev_i32_e32 v3, 31, v2
	v_lshl_add_u64 v[14:15], v[2:3], 1, v[0:1]
	global_store_dwordx4 v[14:15], v[16:19], off
	s_waitcnt vmcnt(19)
	v_mov_b32_e32 v217, v211
	v_lshlrev_b32_e32 v234, 16, v20
	v_and_b32_e32 v20, 0xffff0000, v20
	v_mul_f32_e32 v238, v20, v20
	v_lshlrev_b32_e32 v235, 16, v21
	v_fmac_f32_e32 v238, v234, v234
	v_and_b32_e32 v21, 0xffff0000, v21
	v_fmac_f32_e32 v238, v235, v235
	v_lshlrev_b32_e32 v236, 16, v22
	v_fmac_f32_e32 v238, v21, v21
	v_and_b32_e32 v22, 0xffff0000, v22
	v_fmac_f32_e32 v238, v236, v236
	v_lshlrev_b32_e32 v237, 16, v23
	v_fmac_f32_e32 v238, v22, v22
	v_and_b32_e32 v23, 0xffff0000, v23
	v_fmac_f32_e32 v238, v237, v237
	v_fmac_f32_e32 v238, v23, v23
	ds_bpermute_b32 v239, v204, v238
	s_waitcnt lgkmcnt(0)
	v_add_f32_e32 v238, v238, v239
	ds_bpermute_b32 v239, v205, v238
	s_waitcnt lgkmcnt(0)
	v_add_f32_e32 v238, v238, v239
	ds_bpermute_b32 v239, v214, v238
	s_waitcnt lgkmcnt(0)
	v_add_f32_e32 v238, v238, v239
	ds_bpermute_b32 v239, v215, v238
	s_waitcnt lgkmcnt(0)
	v_add_f32_e32 v238, v238, v239
	v_fmamk_f32 v238, v238, 0x3c000000, v208
	v_mul_f32_e32 v239, 0x4f800000, v238
	v_cmp_gt_f32_e32 vcc, s33, v238
	s_nop 1
	v_cndmask_b32_e32 v238, v238, v239, vcc
	v_sqrt_f32_e32 v239, v238
	s_nop 0
	v_add_u32_e32 v240, -1, v239
	v_add_u32_e32 v241, 1, v239
	v_fma_f32 v242, -v240, v239, v238
	v_fma_f32 v243, -v241, v239, v238
	v_cmp_ge_f32_e64 s[0:1], 0, v242
	s_nop 1
	v_cndmask_b32_e64 v239, v239, v240, s[0:1]
	v_cmp_lt_f32_e64 s[0:1], 0, v243
	s_nop 1
	v_cndmask_b32_e64 v239, v239, v241, s[0:1]
	v_mul_f32_e32 v240, 0x37800000, v239
	v_cndmask_b32_e32 v239, v239, v240, vcc
	v_cmp_class_f32_e32 vcc, v238, v209
	s_nop 1
	v_cndmask_b32_e32 v238, v239, v238, vcc
	v_div_scale_f32 v239, s[0:1], v238, v238, 1.0
	v_rcp_f32_e32 v241, v239
	v_div_scale_f32 v240, vcc, 1.0, v238, 1.0
	v_fma_f32 v242, -v239, v241, 1.0
	v_fmac_f32_e32 v241, v242, v241
	v_mul_f32_e32 v242, v240, v241
	v_fma_f32 v243, -v239, v242, v240
	v_fmac_f32_e32 v242, v243, v241
	v_fma_f32 v239, -v239, v242, v240
	v_div_fmas_f32 v239, v239, v241, v242
	v_div_fixup_f32 v238, v239, v238, 1.0
	v_mul_f32_e32 v217, v217, v238
	v_mul_f32_e32 v20, v217, v20
	v_mul_f32_e32 v21, v217, v21
	v_mul_f32_e32 v22, v217, v22
	v_mul_f32_e32 v23, v217, v23
	v_mul_f32_e32 v234, v217, v234
	v_mul_f32_e32 v235, v217, v235
	v_mul_f32_e32 v236, v217, v236
	v_mul_f32_e32 v237, v217, v237
	v_mul_f32_e32 v20, v219, v20
	v_mul_f32_e32 v21, v221, v21
	v_mul_f32_e32 v22, v223, v22
	v_mul_f32_e32 v23, v225, v23
	v_mul_f32_e32 v244, v218, v234
	v_mul_f32_e32 v245, v220, v235
	v_mul_f32_e32 v246, v222, v236
	v_mul_f32_e32 v247, v224, v237
	v_cvt_pk_bf16_f32 v20, v244, v20
	v_cvt_pk_bf16_f32 v21, v245, v21
	v_cvt_pk_bf16_f32 v22, v246, v22
	v_cvt_pk_bf16_f32 v23, v247, v23
	v_add_u32_e32 v2, 0x200, v216
	v_ashrrev_i32_e32 v3, 31, v2
	v_lshl_add_u64 v[14:15], v[2:3], 1, v[0:1]
	global_store_dwordx4 v[14:15], v[20:23], off
	s_waitcnt vmcnt(19)
	v_mov_b32_e32 v217, v211
	v_lshlrev_b32_e32 v234, 16, v24
	v_and_b32_e32 v24, 0xffff0000, v24
	v_mul_f32_e32 v238, v24, v24
	v_lshlrev_b32_e32 v235, 16, v25
	v_fmac_f32_e32 v238, v234, v234
	v_and_b32_e32 v25, 0xffff0000, v25
	v_fmac_f32_e32 v238, v235, v235
	v_lshlrev_b32_e32 v236, 16, v26
	v_fmac_f32_e32 v238, v25, v25
	v_and_b32_e32 v26, 0xffff0000, v26
	v_fmac_f32_e32 v238, v236, v236
	v_lshlrev_b32_e32 v237, 16, v27
	v_fmac_f32_e32 v238, v26, v26
	v_and_b32_e32 v27, 0xffff0000, v27
	v_fmac_f32_e32 v238, v237, v237
	v_fmac_f32_e32 v238, v27, v27
	ds_bpermute_b32 v239, v204, v238
	s_waitcnt lgkmcnt(0)
	v_add_f32_e32 v238, v238, v239
	ds_bpermute_b32 v239, v205, v238
	s_waitcnt lgkmcnt(0)
	v_add_f32_e32 v238, v238, v239
	ds_bpermute_b32 v239, v214, v238
	s_waitcnt lgkmcnt(0)
	v_add_f32_e32 v238, v238, v239
	ds_bpermute_b32 v239, v215, v238
	s_waitcnt lgkmcnt(0)
; __device__ __forceinline__ unsigned pk2(float lo, float hi) { return pg8::cvt_pk_bf16(lo, hi); }
; __device__ __forceinline__ void idx_unit(bf16* QB, float* SC, int* SEL, const float* qg, const float* kg, int b, int tp, LAS unsigned char* wl, int lane, bool do_norm) {
;     ...
;             const int col = (p < 4) ? (CQ + (4 * p + lg) * 128) : (CK + lg * 128);
;             bf16* ptr = QB + (row + a) * NBP + col + 8 * li;
;             const u32x4 w = *(const u32x4*)ptr;
;             float v[8] = {bflo(w.x), bfhi(w.x), bflo(w.y), bfhi(w.y), bflo(w.z), bfhi(w.z), bflo(w.w), bfhi(w.w)};
;             float s = 0.f;
; #pragma unroll
;             for (int e = 0; e < 8; ++e) s += v[e] * v[e];
;             s += __shfl_xor(s, 1); s += __shfl_xor(s, 2); s += __shfl_xor(s, 4); s += __shfl_xor(s, 8);
;             const float rstd = (1.0f / sqrtf(s * (1.f / 128.f) + RMS_EPS)) * ((p < 4) ? C2 : 1.f);
;             const float* gp = ((p < 4) ? qg : kg) + 8 * li;
;             const f32x4 g0 = *(const f32x4*)gp, g1 = *(const f32x4*)(gp + 4);
;             u32x4 o; o.x = pk2(v[0] * rstd * g0.x, v[1] * rstd * g0.y); o.y = pk2(v[2] * rstd * g0.z, v[3] * rstd * g0.w);
;             o.z = pk2(v[4] * rstd * g1.x, v[5] * rstd * g1.y); o.w = pk2(v[6] * rstd * g1.z, v[7] * rstd * g1.w);
;             *(u32x4*)ptr = o;
	v_add_f32_e32 v238, v238, v239
	v_fmamk_f32 v238, v238, 0x3c000000, v208
	v_mul_f32_e32 v239, 0x4f800000, v238
	v_cmp_gt_f32_e32 vcc, s33, v238
	s_nop 1
	v_cndmask_b32_e32 v238, v238, v239, vcc
	v_sqrt_f32_e32 v239, v238
	s_nop 0
	v_add_u32_e32 v240, -1, v239
	v_add_u32_e32 v241, 1, v239
	v_fma_f32 v242, -v240, v239, v238
	v_fma_f32 v243, -v241, v239, v238
	v_cmp_ge_f32_e64 s[0:1], 0, v242
	s_nop 1
	v_cndmask_b32_e64 v239, v239, v240, s[0:1]
	v_cmp_lt_f32_e64 s[0:1], 0, v243
	s_nop 1
	v_cndmask_b32_e64 v239, v239, v241, s[0:1]
	v_mul_f32_e32 v240, 0x37800000, v239
	v_cndmask_b32_e32 v239, v239, v240, vcc
	v_cmp_class_f32_e32 vcc, v238, v209
	s_nop 1
	v_cndmask_b32_e32 v238, v239, v238, vcc
	v_div_scale_f32 v239, s[0:1], v238, v238, 1.0
	v_rcp_f32_e32 v241, v239
	v_div_scale_f32 v240, vcc, 1.0, v238, 1.0
	v_fma_f32 v242, -v239, v241, 1.0
	v_fmac_f32_e32 v241, v242, v241
	v_mul_f32_e32 v242, v240, v241
	v_fma_f32 v243, -v239, v242, v240
	v_fmac_f32_e32 v242, v243, v241
	v_fma_f32 v239, -v239, v242, v240
	v_div_fmas_f32 v239, v239, v241, v242
	v_div_fixup_f32 v238, v239, v238, 1.0
	v_mul_f32_e32 v217, v217, v238
	v_mul_f32_e32 v24, v217, v24
	v_mul_f32_e32 v25, v217, v25
	v_mul_f32_e32 v26, v217, v26
	v_mul_f32_e32 v27, v217, v27
	v_mul_f32_e32 v234, v217, v234
	v_mul_f32_e32 v235, v217, v235
	v_mul_f32_e32 v236, v217, v236
	v_mul_f32_e32 v237, v217, v237
	v_mul_f32_e32 v24, v219, v24
	v_mul_f32_e32 v25, v221, v25
	v_mul_f32_e32 v26, v223, v26
	v_mul_f32_e32 v27, v225, v27
	v_mul_f32_e32 v244, v218, v234
	v_mul_f32_e32 v245, v220, v235
	v_mul_f32_e32 v246, v222, v236
	v_mul_f32_e32 v247, v224, v237
	v_cvt_pk_bf16_f32 v24, v244, v24
	v_cvt_pk_bf16_f32 v25, v245, v25
	v_cvt_pk_bf16_f32 v26, v246, v26
	v_cvt_pk_bf16_f32 v27, v247, v27
	v_add_u32_e32 v2, 0x400, v216
	v_ashrrev_i32_e32 v3, 31, v2
	v_lshl_add_u64 v[14:15], v[2:3], 1, v[0:1]
	global_store_dwordx4 v[14:15], v[24:27], off
	s_waitcnt vmcnt(19)
	v_mov_b32_e32 v217, v211
	v_lshlrev_b32_e32 v234, 16, v28
	v_and_b32_e32 v28, 0xffff0000, v28
	v_mul_f32_e32 v238, v28, v28
	v_lshlrev_b32_e32 v235, 16, v29
	v_fmac_f32_e32 v238, v234, v234
	v_and_b32_e32 v29, 0xffff0000, v29
	v_fmac_f32_e32 v238, v235, v235
	v_lshlrev_b32_e32 v236, 16, v30
	v_fmac_f32_e32 v238, v29, v29
	v_and_b32_e32 v30, 0xffff0000, v30
	v_fmac_f32_e32 v238, v236, v236
	v_lshlrev_b32_e32 v237, 16, v31
	v_fmac_f32_e32 v238, v30, v30
	v_and_b32_e32 v31, 0xffff0000, v31
	v_fmac_f32_e32 v238, v237, v237
	v_fmac_f32_e32 v238, v31, v31
	ds_bpermute_b32 v239, v204, v238
	s_waitcnt lgkmcnt(0)
	v_add_f32_e32 v238, v238, v239
	ds_bpermute_b32 v239, v205, v238
	s_waitcnt lgkmcnt(0)
	v_add_f32_e32 v238, v238, v239
	ds_bpermute_b32 v239, v214, v238
	s_waitcnt lgkmcnt(0)
	v_add_f32_e32 v238, v238, v239
	ds_bpermute_b32 v239, v215, v238
	s_waitcnt lgkmcnt(0)
	v_add_f32_e32 v238, v238, v239
	v_fmamk_f32 v238, v238, 0x3c000000, v208
	v_mul_f32_e32 v239, 0x4f800000, v238
	v_cmp_gt_f32_e32 vcc, s33, v238
	s_nop 1
	v_cndmask_b32_e32 v238, v238, v239, vcc
	v_sqrt_f32_e32 v239, v238
	s_nop 0
	v_add_u32_e32 v240, -1, v239
	v_add_u32_e32 v241, 1, v239
	v_fma_f32 v242, -v240, v239, v238
	v_fma_f32 v243, -v241, v239, v238
	v_cmp_ge_f32_e64 s[0:1], 0, v242
	s_nop 1
	v_cndmask_b32_e64 v239, v239, v240, s[0:1]
	v_cmp_lt_f32_e64 s[0:1], 0, v243
	s_nop 1
	v_cndmask_b32_e64 v239, v239, v241, s[0:1]
	v_mul_f32_e32 v240, 0x37800000, v239
	v_cndmask_b32_e32 v239, v239, v240, vcc
	v_cmp_class_f32_e32 vcc, v238, v209
	s_nop 1
	v_cndmask_b32_e32 v238, v239, v238, vcc
	v_div_scale_f32 v239, s[0:1], v238, v238, 1.0
	v_rcp_f32_e32 v241, v239
	v_div_scale_f32 v240, vcc, 1.0, v238, 1.0
	v_fma_f32 v242, -v239, v241, 1.0
	v_fmac_f32_e32 v241, v242, v241
	v_mul_f32_e32 v242, v240, v241
	v_fma_f32 v243, -v239, v242, v240
	v_fmac_f32_e32 v242, v243, v241
	v_fma_f32 v239, -v239, v242, v240
	v_div_fmas_f32 v239, v239, v241, v242
	v_div_fixup_f32 v238, v239, v238, 1.0
	v_mul_f32_e32 v217, v217, v238
	v_mul_f32_e32 v28, v217, v28
	v_mul_f32_e32 v29, v217, v29
	v_mul_f32_e32 v30, v217, v30
	v_mul_f32_e32 v31, v217, v31
	v_mul_f32_e32 v234, v217, v234
	v_mul_f32_e32 v235, v217, v235
	v_mul_f32_e32 v236, v217, v236
	v_mul_f32_e32 v237, v217, v237
	v_mul_f32_e32 v28, v219, v28
	v_mul_f32_e32 v29, v221, v29
	v_mul_f32_e32 v30, v223, v30
	v_mul_f32_e32 v31, v225, v31
	v_mul_f32_e32 v244, v218, v234
	v_mul_f32_e32 v245, v220, v235
	v_mul_f32_e32 v246, v222, v236
	v_mul_f32_e32 v247, v224, v237
	v_cvt_pk_bf16_f32 v28, v244, v28
	v_cvt_pk_bf16_f32 v29, v245, v29
	v_cvt_pk_bf16_f32 v30, v246, v30
	v_cvt_pk_bf16_f32 v31, v247, v31
	v_add_u32_e32 v2, 0x600, v216
	v_ashrrev_i32_e32 v3, 31, v2
	v_lshl_add_u64 v[14:15], v[2:3], 1, v[0:1]
	global_store_dwordx4 v[14:15], v[28:31], off
	s_waitcnt vmcnt(19)
	v_mov_b32_e32 v217, 1.0
	v_lshlrev_b32_e32 v234, 16, v32
	v_and_b32_e32 v32, 0xffff0000, v32
	v_mul_f32_e32 v238, v32, v32
	v_lshlrev_b32_e32 v235, 16, v33
	v_fmac_f32_e32 v238, v234, v234
	v_and_b32_e32 v33, 0xffff0000, v33
	v_fmac_f32_e32 v238, v235, v235
	v_lshlrev_b32_e32 v236, 16, v34
	v_fmac_f32_e32 v238, v33, v33
	v_and_b32_e32 v34, 0xffff0000, v34
	v_fmac_f32_e32 v238, v236, v236
	v_lshlrev_b32_e32 v237, 16, v35
	v_fmac_f32_e32 v238, v34, v34
	v_and_b32_e32 v35, 0xffff0000, v35
	v_fmac_f32_e32 v238, v237, v237
	v_fmac_f32_e32 v238, v35, v35
	ds_bpermute_b32 v239, v204, v238
	s_waitcnt lgkmcnt(0)
	v_add_f32_e32 v238, v238, v239
	ds_bpermute_b32 v239, v205, v238
	s_waitcnt lgkmcnt(0)
	v_add_f32_e32 v238, v238, v239
	ds_bpermute_b32 v239, v214, v238
	s_waitcnt lgkmcnt(0)
	v_add_f32_e32 v238, v238, v239
	ds_bpermute_b32 v239, v215, v238
	s_waitcnt lgkmcnt(0)
; __device__ __forceinline__ unsigned pk2(float lo, float hi) { return pg8::cvt_pk_bf16(lo, hi); }
; __device__ __forceinline__ void idx_unit(bf16* QB, float* SC, int* SEL, const float* qg, const float* kg, int b, int tp, LAS unsigned char* wl, int lane, bool do_norm) {
;     ...
;             const int col = (p < 4) ? (CQ + (4 * p + lg) * 128) : (CK + lg * 128);
;             bf16* ptr = QB + (row + a) * NBP + col + 8 * li;
;             const u32x4 w = *(const u32x4*)ptr;
;             float v[8] = {bflo(w.x), bfhi(w.x), bflo(w.y), bfhi(w.y), bflo(w.z), bfhi(w.z), bflo(w.w), bfhi(w.w)};
;             float s = 0.f;
; #pragma unroll
;             for (int e = 0; e < 8; ++e) s += v[e] * v[e];
;             s += __shfl_xor(s, 1); s += __shfl_xor(s, 2); s += __shfl_xor(s, 4); s += __shfl_xor(s, 8);
;             const float rstd = (1.0f / sqrtf(s * (1.f / 128.f) + RMS_EPS)) * ((p < 4) ? C2 : 1.f);
;             const float* gp = ((p < 4) ? qg : kg) + 8 * li;
;             const f32x4 g0 = *(const f32x4*)gp, g1 = *(const f32x4*)(gp + 4);
;             u32x4 o; o.x = pk2(v[0] * rstd * g0.x, v[1] * rstd * g0.y); o.y = pk2(v[2] * rstd * g0.z, v[3] * rstd * g0.w);
;             o.z = pk2(v[4] * rstd * g1.x, v[5] * rstd * g1.y); o.w = pk2(v[6] * rstd * g1.z, v[7] * rstd * g1.w);
;             *(u32x4*)ptr = o;
	v_add_f32_e32 v238, v238, v239
	v_fmamk_f32 v238, v238, 0x3c000000, v208
	v_mul_f32_e32 v239, 0x4f800000, v238
	v_cmp_gt_f32_e32 vcc, s33, v238
	s_nop 1
	v_cndmask_b32_e32 v238, v238, v239, vcc
	v_sqrt_f32_e32 v239, v238
	s_nop 0
	v_add_u32_e32 v240, -1, v239
	v_add_u32_e32 v241, 1, v239
	v_fma_f32 v242, -v240, v239, v238
	v_fma_f32 v243, -v241, v239, v238
	v_cmp_ge_f32_e64 s[0:1], 0, v242
	s_nop 1
	v_cndmask_b32_e64 v239, v239, v240, s[0:1]
	v_cmp_lt_f32_e64 s[0:1], 0, v243
	s_nop 1
	v_cndmask_b32_e64 v239, v239, v241, s[0:1]
	v_mul_f32_e32 v240, 0x37800000, v239
	v_cndmask_b32_e32 v239, v239, v240, vcc
	v_cmp_class_f32_e32 vcc, v238, v209
	s_nop 1
	v_cndmask_b32_e32 v238, v239, v238, vcc
	v_div_scale_f32 v239, s[0:1], v238, v238, 1.0
	v_rcp_f32_e32 v241, v239
	v_div_scale_f32 v240, vcc, 1.0, v238, 1.0
	v_fma_f32 v242, -v239, v241, 1.0
	v_fmac_f32_e32 v241, v242, v241
	v_mul_f32_e32 v242, v240, v241
	v_fma_f32 v243, -v239, v242, v240
	v_fmac_f32_e32 v242, v243, v241
	v_fma_f32 v239, -v239, v242, v240
	v_div_fmas_f32 v239, v239, v241, v242
	v_div_fixup_f32 v238, v239, v238, 1.0
	v_mul_f32_e32 v217, v217, v238
	v_mul_f32_e32 v32, v217, v32
	v_mul_f32_e32 v33, v217, v33
	v_mul_f32_e32 v34, v217, v34
	v_mul_f32_e32 v35, v217, v35
	v_mul_f32_e32 v234, v217, v234
	v_mul_f32_e32 v235, v217, v235
	v_mul_f32_e32 v236, v217, v236
	v_mul_f32_e32 v237, v217, v237
	v_mul_f32_e32 v32, v227, v32
	v_mul_f32_e32 v33, v229, v33
	v_mul_f32_e32 v34, v231, v34
	v_mul_f32_e32 v35, v233, v35
	v_mul_f32_e32 v244, v226, v234
	v_mul_f32_e32 v245, v228, v235
	v_mul_f32_e32 v246, v230, v236
	v_mul_f32_e32 v247, v232, v237
	v_cvt_pk_bf16_f32 v32, v244, v32
	v_cvt_pk_bf16_f32 v33, v245, v33
	v_cvt_pk_bf16_f32 v34, v246, v34
	v_cvt_pk_bf16_f32 v35, v247, v35
	v_add_u32_e32 v2, 0x800, v216
	v_ashrrev_i32_e32 v3, 31, v2
	v_lshl_add_u64 v[14:15], v[2:3], 1, v[0:1]
	global_store_dwordx4 v[14:15], v[32:35], off
	s_add_u32 s0, s2, 1
	s_addc_u32 s1, s79, 0
	s_mul_i32 s4, s1, 0x2200
	v_mad_u64_u32 v[0:1], s[0:1], s0, v212, v[118:119]
	v_add_u32_e32 v1, s4, v1
	s_waitcnt vmcnt(19)
	v_mov_b32_e32 v217, v211
	v_lshlrev_b32_e32 v234, 16, v36
	v_and_b32_e32 v36, 0xffff0000, v36
	v_mul_f32_e32 v238, v36, v36
	v_lshlrev_b32_e32 v235, 16, v37
	v_fmac_f32_e32 v238, v234, v234
	v_and_b32_e32 v37, 0xffff0000, v37
	v_fmac_f32_e32 v238, v235, v235
	v_lshlrev_b32_e32 v236, 16, v38
	v_fmac_f32_e32 v238, v37, v37
	v_and_b32_e32 v38, 0xffff0000, v38
	v_fmac_f32_e32 v238, v236, v236
	v_lshlrev_b32_e32 v237, 16, v39
	v_fmac_f32_e32 v238, v38, v38
	v_and_b32_e32 v39, 0xffff0000, v39
	v_fmac_f32_e32 v238, v237, v237
	v_fmac_f32_e32 v238, v39, v39
	ds_bpermute_b32 v239, v204, v238
	s_waitcnt lgkmcnt(0)
	v_add_f32_e32 v238, v238, v239
	ds_bpermute_b32 v239, v205, v238
	s_waitcnt lgkmcnt(0)
	v_add_f32_e32 v238, v238, v239
	ds_bpermute_b32 v239, v214, v238
	s_waitcnt lgkmcnt(0)
	v_add_f32_e32 v238, v238, v239
	ds_bpermute_b32 v239, v215, v238
	s_waitcnt lgkmcnt(0)
	v_add_f32_e32 v238, v238, v239
	v_fmamk_f32 v238, v238, 0x3c000000, v208
	v_mul_f32_e32 v239, 0x4f800000, v238
	v_cmp_gt_f32_e32 vcc, s33, v238
	s_nop 1
	v_cndmask_b32_e32 v238, v238, v239, vcc
	v_sqrt_f32_e32 v239, v238
	s_nop 0
	v_add_u32_e32 v240, -1, v239
	v_add_u32_e32 v241, 1, v239
	v_fma_f32 v242, -v240, v239, v238
	v_fma_f32 v243, -v241, v239, v238
	v_cmp_ge_f32_e64 s[0:1], 0, v242
	s_nop 1
	v_cndmask_b32_e64 v239, v239, v240, s[0:1]
	v_cmp_lt_f32_e64 s[0:1], 0, v243
	s_nop 1
	v_cndmask_b32_e64 v239, v239, v241, s[0:1]
	v_mul_f32_e32 v240, 0x37800000, v239
	v_cndmask_b32_e32 v239, v239, v240, vcc
	v_cmp_class_f32_e32 vcc, v238, v209
	s_nop 1
	v_cndmask_b32_e32 v238, v239, v238, vcc
	v_div_scale_f32 v239, s[0:1], v238, v238, 1.0
	v_rcp_f32_e32 v241, v239
	v_div_scale_f32 v240, vcc, 1.0, v238, 1.0
	v_fma_f32 v242, -v239, v241, 1.0
	v_fmac_f32_e32 v241, v242, v241
	v_mul_f32_e32 v242, v240, v241
	v_fma_f32 v243, -v239, v242, v240
	v_fmac_f32_e32 v242, v243, v241
	v_fma_f32 v239, -v239, v242, v240
	v_div_fmas_f32 v239, v239, v241, v242
	v_div_fixup_f32 v238, v239, v238, 1.0
	v_mul_f32_e32 v217, v217, v238
	v_mul_f32_e32 v36, v217, v36
	v_mul_f32_e32 v37, v217, v37
	v_mul_f32_e32 v38, v217, v38
	v_mul_f32_e32 v39, v217, v39
	v_mul_f32_e32 v234, v217, v234
	v_mul_f32_e32 v235, v217, v235
	v_mul_f32_e32 v236, v217, v236
	v_mul_f32_e32 v237, v217, v237
	v_mul_f32_e32 v36, v219, v36
	v_mul_f32_e32 v37, v221, v37
	v_mul_f32_e32 v38, v223, v38
	v_mul_f32_e32 v39, v225, v39
	v_mul_f32_e32 v244, v218, v234
	v_mul_f32_e32 v245, v220, v235
	v_mul_f32_e32 v246, v222, v236
	v_mul_f32_e32 v247, v224, v237
	v_cvt_pk_bf16_f32 v36, v244, v36
	v_cvt_pk_bf16_f32 v37, v245, v37
	v_cvt_pk_bf16_f32 v38, v246, v38
	v_cvt_pk_bf16_f32 v39, v247, v39
	v_mov_b32_e32 v2, v216
	v_ashrrev_i32_e32 v3, 31, v2
	v_lshl_add_u64 v[14:15], v[2:3], 1, v[0:1]
	global_store_dwordx4 v[14:15], v[36:39], off
	s_waitcnt vmcnt(19)
	v_mov_b32_e32 v217, v211
	v_lshlrev_b32_e32 v234, 16, v40
	v_and_b32_e32 v40, 0xffff0000, v40
	v_mul_f32_e32 v238, v40, v40
	v_lshlrev_b32_e32 v235, 16, v41
	v_fmac_f32_e32 v238, v234, v234
	v_and_b32_e32 v41, 0xffff0000, v41
	v_fmac_f32_e32 v238, v235, v235
	v_lshlrev_b32_e32 v236, 16, v42
	v_fmac_f32_e32 v238, v41, v41
	v_and_b32_e32 v42, 0xffff0000, v42
	v_fmac_f32_e32 v238, v236, v236
	v_lshlrev_b32_e32 v237, 16, v43
	v_fmac_f32_e32 v238, v42, v42
	v_and_b32_e32 v43, 0xffff0000, v43
	v_fmac_f32_e32 v238, v237, v237
	v_fmac_f32_e32 v238, v43, v43
	ds_bpermute_b32 v239, v204, v238
	s_waitcnt lgkmcnt(0)
	v_add_f32_e32 v238, v238, v239
	ds_bpermute_b32 v239, v205, v238
	s_waitcnt lgkmcnt(0)
	v_add_f32_e32 v238, v238, v239
	ds_bpermute_b32 v239, v214, v238
	s_waitcnt lgkmcnt(0)
; __device__ __forceinline__ unsigned pk2(float lo, float hi) { return pg8::cvt_pk_bf16(lo, hi); }
; __device__ __forceinline__ void idx_unit(bf16* QB, float* SC, int* SEL, const float* qg, const float* kg, int b, int tp, LAS unsigned char* wl, int lane, bool do_norm) {
;     ...
;             const int col = (p < 4) ? (CQ + (4 * p + lg) * 128) : (CK + lg * 128);
;             bf16* ptr = QB + (row + a) * NBP + col + 8 * li;
;             const u32x4 w = *(const u32x4*)ptr;
;             float v[8] = {bflo(w.x), bfhi(w.x), bflo(w.y), bfhi(w.y), bflo(w.z), bfhi(w.z), bflo(w.w), bfhi(w.w)};
;             float s = 0.f;
; #pragma unroll
;             for (int e = 0; e < 8; ++e) s += v[e] * v[e];
;             s += __shfl_xor(s, 1); s += __shfl_xor(s, 2); s += __shfl_xor(s, 4); s += __shfl_xor(s, 8);
;             const float rstd = (1.0f / sqrtf(s * (1.f / 128.f) + RMS_EPS)) * ((p < 4) ? C2 : 1.f);
;             const float* gp = ((p < 4) ? qg : kg) + 8 * li;
;             const f32x4 g0 = *(const f32x4*)gp, g1 = *(const f32x4*)(gp + 4);
;             u32x4 o; o.x = pk2(v[0] * rstd * g0.x, v[1] * rstd * g0.y); o.y = pk2(v[2] * rstd * g0.z, v[3] * rstd * g0.w);
;             o.z = pk2(v[4] * rstd * g1.x, v[5] * rstd * g1.y); o.w = pk2(v[6] * rstd * g1.z, v[7] * rstd * g1.w);
;             *(u32x4*)ptr = o;
	v_add_f32_e32 v238, v238, v239
	ds_bpermute_b32 v239, v215, v238
	s_waitcnt lgkmcnt(0)
	v_add_f32_e32 v238, v238, v239
	v_fmamk_f32 v238, v238, 0x3c000000, v208
	v_mul_f32_e32 v239, 0x4f800000, v238
	v_cmp_gt_f32_e32 vcc, s33, v238
	s_nop 1
	v_cndmask_b32_e32 v238, v238, v239, vcc
	v_sqrt_f32_e32 v239, v238
	s_nop 0
	v_add_u32_e32 v240, -1, v239
	v_add_u32_e32 v241, 1, v239
	v_fma_f32 v242, -v240, v239, v238
	v_fma_f32 v243, -v241, v239, v238
	v_cmp_ge_f32_e64 s[0:1], 0, v242
	s_nop 1
	v_cndmask_b32_e64 v239, v239, v240, s[0:1]
	v_cmp_lt_f32_e64 s[0:1], 0, v243
	s_nop 1
	v_cndmask_b32_e64 v239, v239, v241, s[0:1]
	v_mul_f32_e32 v240, 0x37800000, v239
	v_cndmask_b32_e32 v239, v239, v240, vcc
	v_cmp_class_f32_e32 vcc, v238, v209
	s_nop 1
	v_cndmask_b32_e32 v238, v239, v238, vcc
	v_div_scale_f32 v239, s[0:1], v238, v238, 1.0
	v_rcp_f32_e32 v241, v239
	v_div_scale_f32 v240, vcc, 1.0, v238, 1.0
	v_fma_f32 v242, -v239, v241, 1.0
	v_fmac_f32_e32 v241, v242, v241
	v_mul_f32_e32 v242, v240, v241
	v_fma_f32 v243, -v239, v242, v240
	v_fmac_f32_e32 v242, v243, v241
	v_fma_f32 v239, -v239, v242, v240
	v_div_fmas_f32 v239, v239, v241, v242
	v_div_fixup_f32 v238, v239, v238, 1.0
	v_mul_f32_e32 v217, v217, v238
	v_mul_f32_e32 v40, v217, v40
	v_mul_f32_e32 v41, v217, v41
	v_mul_f32_e32 v42, v217, v42
	v_mul_f32_e32 v43, v217, v43
	v_mul_f32_e32 v234, v217, v234
	v_mul_f32_e32 v235, v217, v235
	v_mul_f32_e32 v236, v217, v236
	v_mul_f32_e32 v237, v217, v237
	v_mul_f32_e32 v40, v219, v40
	v_mul_f32_e32 v41, v221, v41
	v_mul_f32_e32 v42, v223, v42
	v_mul_f32_e32 v43, v225, v43
	v_mul_f32_e32 v244, v218, v234
	v_mul_f32_e32 v245, v220, v235
	v_mul_f32_e32 v246, v222, v236
	v_mul_f32_e32 v247, v224, v237
	v_cvt_pk_bf16_f32 v40, v244, v40
	v_cvt_pk_bf16_f32 v41, v245, v41
	v_cvt_pk_bf16_f32 v42, v246, v42
	v_cvt_pk_bf16_f32 v43, v247, v43
	v_add_u32_e32 v2, 0x200, v216
	v_ashrrev_i32_e32 v3, 31, v2
	v_lshl_add_u64 v[14:15], v[2:3], 1, v[0:1]
	global_store_dwordx4 v[14:15], v[40:43], off
	s_waitcnt vmcnt(19)
	v_mov_b32_e32 v217, v211
	v_lshlrev_b32_e32 v234, 16, v44
	v_and_b32_e32 v44, 0xffff0000, v44
	v_mul_f32_e32 v238, v44, v44
	v_lshlrev_b32_e32 v235, 16, v45
	v_fmac_f32_e32 v238, v234, v234
	v_and_b32_e32 v45, 0xffff0000, v45
	v_fmac_f32_e32 v238, v235, v235
	v_lshlrev_b32_e32 v236, 16, v46
	v_fmac_f32_e32 v238, v45, v45
	v_and_b32_e32 v46, 0xffff0000, v46
	v_fmac_f32_e32 v238, v236, v236
	v_lshlrev_b32_e32 v237, 16, v47
	v_fmac_f32_e32 v238, v46, v46
	v_and_b32_e32 v47, 0xffff0000, v47
	v_fmac_f32_e32 v238, v237, v237
	v_fmac_f32_e32 v238, v47, v47
	ds_bpermute_b32 v239, v204, v238
	s_waitcnt lgkmcnt(0)
	v_add_f32_e32 v238, v238, v239
	ds_bpermute_b32 v239, v205, v238
	s_waitcnt lgkmcnt(0)
	v_add_f32_e32 v238, v238, v239
	ds_bpermute_b32 v239, v214, v238
	s_waitcnt lgkmcnt(0)
	v_add_f32_e32 v238, v238, v239
	ds_bpermute_b32 v239, v215, v238
	s_waitcnt lgkmcnt(0)
	v_add_f32_e32 v238, v238, v239
	v_fmamk_f32 v238, v238, 0x3c000000, v208
	v_mul_f32_e32 v239, 0x4f800000, v238
	v_cmp_gt_f32_e32 vcc, s33, v238
	s_nop 1
	v_cndmask_b32_e32 v238, v238, v239, vcc
	v_sqrt_f32_e32 v239, v238
	s_nop 0
	v_add_u32_e32 v240, -1, v239
	v_add_u32_e32 v241, 1, v239
	v_fma_f32 v242, -v240, v239, v238
	v_fma_f32 v243, -v241, v239, v238
	v_cmp_ge_f32_e64 s[0:1], 0, v242
	s_nop 1
	v_cndmask_b32_e64 v239, v239, v240, s[0:1]
	v_cmp_lt_f32_e64 s[0:1], 0, v243
	s_nop 1
	v_cndmask_b32_e64 v239, v239, v241, s[0:1]
	v_mul_f32_e32 v240, 0x37800000, v239
	v_cndmask_b32_e32 v239, v239, v240, vcc
	v_cmp_class_f32_e32 vcc, v238, v209
	s_nop 1
	v_cndmask_b32_e32 v238, v239, v238, vcc
	v_div_scale_f32 v239, s[0:1], v238, v238, 1.0
	v_rcp_f32_e32 v241, v239
	v_div_scale_f32 v240, vcc, 1.0, v238, 1.0
	v_fma_f32 v242, -v239, v241, 1.0
	v_fmac_f32_e32 v241, v242, v241
	v_mul_f32_e32 v242, v240, v241
	v_fma_f32 v243, -v239, v242, v240
	v_fmac_f32_e32 v242, v243, v241
	v_fma_f32 v239, -v239, v242, v240
	v_div_fmas_f32 v239, v239, v241, v242
	v_div_fixup_f32 v238, v239, v238, 1.0
	v_mul_f32_e32 v217, v217, v238
	v_mul_f32_e32 v44, v217, v44
	v_mul_f32_e32 v45, v217, v45
	v_mul_f32_e32 v46, v217, v46
	v_mul_f32_e32 v47, v217, v47
	v_mul_f32_e32 v234, v217, v234
	v_mul_f32_e32 v235, v217, v235
	v_mul_f32_e32 v236, v217, v236
	v_mul_f32_e32 v237, v217, v237
	v_mul_f32_e32 v44, v219, v44
	v_mul_f32_e32 v45, v221, v45
	v_mul_f32_e32 v46, v223, v46
	v_mul_f32_e32 v47, v225, v47
	v_mul_f32_e32 v244, v218, v234
	v_mul_f32_e32 v245, v220, v235
	v_mul_f32_e32 v246, v222, v236
	v_mul_f32_e32 v247, v224, v237
	v_cvt_pk_bf16_f32 v44, v244, v44
	v_cvt_pk_bf16_f32 v45, v245, v45
	v_cvt_pk_bf16_f32 v46, v246, v46
	v_cvt_pk_bf16_f32 v47, v247, v47
	v_add_u32_e32 v2, 0x400, v216
	v_ashrrev_i32_e32 v3, 31, v2
	v_lshl_add_u64 v[14:15], v[2:3], 1, v[0:1]
	global_store_dwordx4 v[14:15], v[44:47], off
	s_waitcnt vmcnt(19)
	v_mov_b32_e32 v217, v211
	v_lshlrev_b32_e32 v234, 16, v48
	v_and_b32_e32 v48, 0xffff0000, v48
	v_mul_f32_e32 v238, v48, v48
	v_lshlrev_b32_e32 v235, 16, v49
	v_fmac_f32_e32 v238, v234, v234
	v_and_b32_e32 v49, 0xffff0000, v49
	v_fmac_f32_e32 v238, v235, v235
	v_lshlrev_b32_e32 v236, 16, v50
	v_fmac_f32_e32 v238, v49, v49
	v_and_b32_e32 v50, 0xffff0000, v50
	v_fmac_f32_e32 v238, v236, v236
	v_lshlrev_b32_e32 v237, 16, v51
	v_fmac_f32_e32 v238, v50, v50
	v_and_b32_e32 v51, 0xffff0000, v51
	v_fmac_f32_e32 v238, v237, v237
	v_fmac_f32_e32 v238, v51, v51
	ds_bpermute_b32 v239, v204, v238
	s_waitcnt lgkmcnt(0)
	v_add_f32_e32 v238, v238, v239
	ds_bpermute_b32 v239, v205, v238
	s_waitcnt lgkmcnt(0)
	v_add_f32_e32 v238, v238, v239
	ds_bpermute_b32 v239, v214, v238
	s_waitcnt lgkmcnt(0)
; __device__ __forceinline__ unsigned pk2(float lo, float hi) { return pg8::cvt_pk_bf16(lo, hi); }
; __device__ __forceinline__ void idx_unit(bf16* QB, float* SC, int* SEL, const float* qg, const float* kg, int b, int tp, LAS unsigned char* wl, int lane, bool do_norm) {
;     ...
;             const int col = (p < 4) ? (CQ + (4 * p + lg) * 128) : (CK + lg * 128);
;             bf16* ptr = QB + (row + a) * NBP + col + 8 * li;
;             const u32x4 w = *(const u32x4*)ptr;
;             float v[8] = {bflo(w.x), bfhi(w.x), bflo(w.y), bfhi(w.y), bflo(w.z), bfhi(w.z), bflo(w.w), bfhi(w.w)};
;             float s = 0.f;
; #pragma unroll
;             for (int e = 0; e < 8; ++e) s += v[e] * v[e];
;             s += __shfl_xor(s, 1); s += __shfl_xor(s, 2); s += __shfl_xor(s, 4); s += __shfl_xor(s, 8);
;             const float rstd = (1.0f / sqrtf(s * (1.f / 128.f) + RMS_EPS)) * ((p < 4) ? C2 : 1.f);
;             const float* gp = ((p < 4) ? qg : kg) + 8 * li;
;             const f32x4 g0 = *(const f32x4*)gp, g1 = *(const f32x4*)(gp + 4);
;             u32x4 o; o.x = pk2(v[0] * rstd * g0.x, v[1] * rstd * g0.y); o.y = pk2(v[2] * rstd * g0.z, v[3] * rstd * g0.w);
;             o.z = pk2(v[4] * rstd * g1.x, v[5] * rstd * g1.y); o.w = pk2(v[6] * rstd * g1.z, v[7] * rstd * g1.w);
;             *(u32x4*)ptr = o;
	v_add_f32_e32 v238, v238, v239
	ds_bpermute_b32 v239, v215, v238
	s_waitcnt lgkmcnt(0)
	v_add_f32_e32 v238, v238, v239
	v_fmamk_f32 v238, v238, 0x3c000000, v208
	v_mul_f32_e32 v239, 0x4f800000, v238
	v_cmp_gt_f32_e32 vcc, s33, v238
	s_nop 1
	v_cndmask_b32_e32 v238, v238, v239, vcc
	v_sqrt_f32_e32 v239, v238
	s_nop 0
	v_add_u32_e32 v240, -1, v239
	v_add_u32_e32 v241, 1, v239
	v_fma_f32 v242, -v240, v239, v238
	v_fma_f32 v243, -v241, v239, v238
	v_cmp_ge_f32_e64 s[0:1], 0, v242
	s_nop 1
	v_cndmask_b32_e64 v239, v239, v240, s[0:1]
	v_cmp_lt_f32_e64 s[0:1], 0, v243
	s_nop 1
	v_cndmask_b32_e64 v239, v239, v241, s[0:1]
	v_mul_f32_e32 v240, 0x37800000, v239
	v_cndmask_b32_e32 v239, v239, v240, vcc
	v_cmp_class_f32_e32 vcc, v238, v209
	s_nop 1
	v_cndmask_b32_e32 v238, v239, v238, vcc
	v_div_scale_f32 v239, s[0:1], v238, v238, 1.0
	v_rcp_f32_e32 v241, v239
	v_div_scale_f32 v240, vcc, 1.0, v238, 1.0
	v_fma_f32 v242, -v239, v241, 1.0
	v_fmac_f32_e32 v241, v242, v241
	v_mul_f32_e32 v242, v240, v241
	v_fma_f32 v243, -v239, v242, v240
	v_fmac_f32_e32 v242, v243, v241
	v_fma_f32 v239, -v239, v242, v240
	v_div_fmas_f32 v239, v239, v241, v242
	v_div_fixup_f32 v238, v239, v238, 1.0
	v_mul_f32_e32 v217, v217, v238
	v_mul_f32_e32 v48, v217, v48
	v_mul_f32_e32 v49, v217, v49
	v_mul_f32_e32 v50, v217, v50
	v_mul_f32_e32 v51, v217, v51
	v_mul_f32_e32 v234, v217, v234
	v_mul_f32_e32 v235, v217, v235
	v_mul_f32_e32 v236, v217, v236
	v_mul_f32_e32 v237, v217, v237
	v_mul_f32_e32 v48, v219, v48
	v_mul_f32_e32 v49, v221, v49
	v_mul_f32_e32 v50, v223, v50
	v_mul_f32_e32 v51, v225, v51
	v_mul_f32_e32 v244, v218, v234
	v_mul_f32_e32 v245, v220, v235
	v_mul_f32_e32 v246, v222, v236
	v_mul_f32_e32 v247, v224, v237
	v_cvt_pk_bf16_f32 v48, v244, v48
	v_cvt_pk_bf16_f32 v49, v245, v49
	v_cvt_pk_bf16_f32 v50, v246, v50
	v_cvt_pk_bf16_f32 v51, v247, v51
	v_add_u32_e32 v2, 0x600, v216
	v_ashrrev_i32_e32 v3, 31, v2
	v_lshl_add_u64 v[14:15], v[2:3], 1, v[0:1]
	global_store_dwordx4 v[14:15], v[48:51], off
	s_waitcnt vmcnt(19)
	v_mov_b32_e32 v217, 1.0
	v_lshlrev_b32_e32 v234, 16, v52
	v_and_b32_e32 v52, 0xffff0000, v52
	v_mul_f32_e32 v238, v52, v52
	v_lshlrev_b32_e32 v235, 16, v53
	v_fmac_f32_e32 v238, v234, v234
	v_and_b32_e32 v53, 0xffff0000, v53
	v_fmac_f32_e32 v238, v235, v235
	v_lshlrev_b32_e32 v236, 16, v54
	v_fmac_f32_e32 v238, v53, v53
	v_and_b32_e32 v54, 0xffff0000, v54
	v_fmac_f32_e32 v238, v236, v236
	v_lshlrev_b32_e32 v237, 16, v55
	v_fmac_f32_e32 v238, v54, v54
	v_and_b32_e32 v55, 0xffff0000, v55
	v_fmac_f32_e32 v238, v237, v237
	v_fmac_f32_e32 v238, v55, v55
	ds_bpermute_b32 v239, v204, v238
	s_waitcnt lgkmcnt(0)
	v_add_f32_e32 v238, v238, v239
	ds_bpermute_b32 v239, v205, v238
	s_waitcnt lgkmcnt(0)
	v_add_f32_e32 v238, v238, v239
	ds_bpermute_b32 v239, v214, v238
	s_waitcnt lgkmcnt(0)
	v_add_f32_e32 v238, v238, v239
	ds_bpermute_b32 v239, v215, v238
	s_waitcnt lgkmcnt(0)
	v_add_f32_e32 v238, v238, v239
	v_fmamk_f32 v238, v238, 0x3c000000, v208
	v_mul_f32_e32 v239, 0x4f800000, v238
	v_cmp_gt_f32_e32 vcc, s33, v238
	s_nop 1
	v_cndmask_b32_e32 v238, v238, v239, vcc
	v_sqrt_f32_e32 v239, v238
	s_nop 0
	v_add_u32_e32 v240, -1, v239
	v_add_u32_e32 v241, 1, v239
	v_fma_f32 v242, -v240, v239, v238
	v_fma_f32 v243, -v241, v239, v238
	v_cmp_ge_f32_e64 s[0:1], 0, v242
	s_nop 1
	v_cndmask_b32_e64 v239, v239, v240, s[0:1]
	v_cmp_lt_f32_e64 s[0:1], 0, v243
	s_nop 1
	v_cndmask_b32_e64 v239, v239, v241, s[0:1]
	v_mul_f32_e32 v240, 0x37800000, v239
	v_cndmask_b32_e32 v239, v239, v240, vcc
	v_cmp_class_f32_e32 vcc, v238, v209
	s_nop 1
	v_cndmask_b32_e32 v238, v239, v238, vcc
	v_div_scale_f32 v239, s[0:1], v238, v238, 1.0
	v_rcp_f32_e32 v241, v239
	v_div_scale_f32 v240, vcc, 1.0, v238, 1.0
	v_fma_f32 v242, -v239, v241, 1.0
	v_fmac_f32_e32 v241, v242, v241
	v_mul_f32_e32 v242, v240, v241
	v_fma_f32 v243, -v239, v242, v240
	v_fmac_f32_e32 v242, v243, v241
	v_fma_f32 v239, -v239, v242, v240
	v_div_fmas_f32 v239, v239, v241, v242
	v_div_fixup_f32 v238, v239, v238, 1.0
	v_mul_f32_e32 v217, v217, v238
	v_mul_f32_e32 v52, v217, v52
	v_mul_f32_e32 v53, v217, v53
	v_mul_f32_e32 v54, v217, v54
	v_mul_f32_e32 v55, v217, v55
	v_mul_f32_e32 v234, v217, v234
	v_mul_f32_e32 v235, v217, v235
	v_mul_f32_e32 v236, v217, v236
	v_mul_f32_e32 v237, v217, v237
	v_mul_f32_e32 v52, v227, v52
	v_mul_f32_e32 v53, v229, v53
	v_mul_f32_e32 v54, v231, v54
	v_mul_f32_e32 v55, v233, v55
	v_mul_f32_e32 v244, v226, v234
	v_mul_f32_e32 v245, v228, v235
	v_mul_f32_e32 v246, v230, v236
	v_mul_f32_e32 v247, v232, v237
	v_cvt_pk_bf16_f32 v52, v244, v52
	v_cvt_pk_bf16_f32 v53, v245, v53
	v_cvt_pk_bf16_f32 v54, v246, v54
	v_cvt_pk_bf16_f32 v55, v247, v55
	v_add_u32_e32 v2, 0x800, v216
	v_ashrrev_i32_e32 v3, 31, v2
	v_lshl_add_u64 v[14:15], v[2:3], 1, v[0:1]
	global_store_dwordx4 v[14:15], v[52:55], off
	s_add_u32 s0, s2, 2
	s_addc_u32 s1, s79, 0
	s_mul_i32 s4, s1, 0x2200
	v_mad_u64_u32 v[0:1], s[0:1], s0, v212, v[118:119]
	v_add_u32_e32 v1, s4, v1
	s_waitcnt vmcnt(19)
	v_mov_b32_e32 v217, v211
	v_lshlrev_b32_e32 v234, 16, v56
	v_and_b32_e32 v56, 0xffff0000, v56
	v_mul_f32_e32 v238, v56, v56
	v_lshlrev_b32_e32 v235, 16, v57
	v_fmac_f32_e32 v238, v234, v234
	v_and_b32_e32 v57, 0xffff0000, v57
	v_fmac_f32_e32 v238, v235, v235
	v_lshlrev_b32_e32 v236, 16, v58
	v_fmac_f32_e32 v238, v57, v57
	v_and_b32_e32 v58, 0xffff0000, v58
	v_fmac_f32_e32 v238, v236, v236
	v_lshlrev_b32_e32 v237, 16, v59
	v_fmac_f32_e32 v238, v58, v58
	v_and_b32_e32 v59, 0xffff0000, v59
	v_fmac_f32_e32 v238, v237, v237
	v_fmac_f32_e32 v238, v59, v59
	ds_bpermute_b32 v239, v204, v238
	s_waitcnt lgkmcnt(0)
	v_add_f32_e32 v238, v238, v239
	ds_bpermute_b32 v239, v205, v238
	s_waitcnt lgkmcnt(0)
; __device__ __forceinline__ unsigned pk2(float lo, float hi) { return pg8::cvt_pk_bf16(lo, hi); }
; __device__ __forceinline__ void idx_unit(bf16* QB, float* SC, int* SEL, const float* qg, const float* kg, int b, int tp, LAS unsigned char* wl, int lane, bool do_norm) {
;     ...
;             const int col = (p < 4) ? (CQ + (4 * p + lg) * 128) : (CK + lg * 128);
;             bf16* ptr = QB + (row + a) * NBP + col + 8 * li;
;             const u32x4 w = *(const u32x4*)ptr;
;             float v[8] = {bflo(w.x), bfhi(w.x), bflo(w.y), bfhi(w.y), bflo(w.z), bfhi(w.z), bflo(w.w), bfhi(w.w)};
;             float s = 0.f;
; #pragma unroll
;             for (int e = 0; e < 8; ++e) s += v[e] * v[e];
;             s += __shfl_xor(s, 1); s += __shfl_xor(s, 2); s += __shfl_xor(s, 4); s += __shfl_xor(s, 8);
;             const float rstd = (1.0f / sqrtf(s * (1.f / 128.f) + RMS_EPS)) * ((p < 4) ? C2 : 1.f);
;             const float* gp = ((p < 4) ? qg : kg) + 8 * li;
;             const f32x4 g0 = *(const f32x4*)gp, g1 = *(const f32x4*)(gp + 4);
;             u32x4 o; o.x = pk2(v[0] * rstd * g0.x, v[1] * rstd * g0.y); o.y = pk2(v[2] * rstd * g0.z, v[3] * rstd * g0.w);
;             o.z = pk2(v[4] * rstd * g1.x, v[5] * rstd * g1.y); o.w = pk2(v[6] * rstd * g1.z, v[7] * rstd * g1.w);
;             *(u32x4*)ptr = o;
	v_add_f32_e32 v238, v238, v239
	ds_bpermute_b32 v239, v214, v238
	s_waitcnt lgkmcnt(0)
	v_add_f32_e32 v238, v238, v239
	ds_bpermute_b32 v239, v215, v238
	s_waitcnt lgkmcnt(0)
	v_add_f32_e32 v238, v238, v239
	v_fmamk_f32 v238, v238, 0x3c000000, v208
	v_mul_f32_e32 v239, 0x4f800000, v238
	v_cmp_gt_f32_e32 vcc, s33, v238
	s_nop 1
	v_cndmask_b32_e32 v238, v238, v239, vcc
	v_sqrt_f32_e32 v239, v238
	s_nop 0
	v_add_u32_e32 v240, -1, v239
	v_add_u32_e32 v241, 1, v239
	v_fma_f32 v242, -v240, v239, v238
	v_fma_f32 v243, -v241, v239, v238
	v_cmp_ge_f32_e64 s[0:1], 0, v242
	s_nop 1
	v_cndmask_b32_e64 v239, v239, v240, s[0:1]
	v_cmp_lt_f32_e64 s[0:1], 0, v243
	s_nop 1
	v_cndmask_b32_e64 v239, v239, v241, s[0:1]
	v_mul_f32_e32 v240, 0x37800000, v239
	v_cndmask_b32_e32 v239, v239, v240, vcc
	v_cmp_class_f32_e32 vcc, v238, v209
	s_nop 1
	v_cndmask_b32_e32 v238, v239, v238, vcc
	v_div_scale_f32 v239, s[0:1], v238, v238, 1.0
	v_rcp_f32_e32 v241, v239
	v_div_scale_f32 v240, vcc, 1.0, v238, 1.0
	v_fma_f32 v242, -v239, v241, 1.0
	v_fmac_f32_e32 v241, v242, v241
	v_mul_f32_e32 v242, v240, v241
	v_fma_f32 v243, -v239, v242, v240
	v_fmac_f32_e32 v242, v243, v241
	v_fma_f32 v239, -v239, v242, v240
	v_div_fmas_f32 v239, v239, v241, v242
	v_div_fixup_f32 v238, v239, v238, 1.0
	v_mul_f32_e32 v217, v217, v238
	v_mul_f32_e32 v56, v217, v56
	v_mul_f32_e32 v57, v217, v57
	v_mul_f32_e32 v58, v217, v58
	v_mul_f32_e32 v59, v217, v59
	v_mul_f32_e32 v234, v217, v234
	v_mul_f32_e32 v235, v217, v235
	v_mul_f32_e32 v236, v217, v236
	v_mul_f32_e32 v237, v217, v237
	v_mul_f32_e32 v56, v219, v56
	v_mul_f32_e32 v57, v221, v57
	v_mul_f32_e32 v58, v223, v58
	v_mul_f32_e32 v59, v225, v59
	v_mul_f32_e32 v244, v218, v234
	v_mul_f32_e32 v245, v220, v235
	v_mul_f32_e32 v246, v222, v236
	v_mul_f32_e32 v247, v224, v237
	v_cvt_pk_bf16_f32 v56, v244, v56
	v_cvt_pk_bf16_f32 v57, v245, v57
	v_cvt_pk_bf16_f32 v58, v246, v58
	v_cvt_pk_bf16_f32 v59, v247, v59
	v_mov_b32_e32 v2, v216
	v_ashrrev_i32_e32 v3, 31, v2
	v_lshl_add_u64 v[14:15], v[2:3], 1, v[0:1]
	global_store_dwordx4 v[14:15], v[56:59], off
	s_waitcnt vmcnt(19)
	v_mov_b32_e32 v217, v211
	v_lshlrev_b32_e32 v234, 16, v60
	v_and_b32_e32 v60, 0xffff0000, v60
	v_mul_f32_e32 v238, v60, v60
	v_lshlrev_b32_e32 v235, 16, v61
	v_fmac_f32_e32 v238, v234, v234
	v_and_b32_e32 v61, 0xffff0000, v61
	v_fmac_f32_e32 v238, v235, v235
	v_lshlrev_b32_e32 v236, 16, v62
	v_fmac_f32_e32 v238, v61, v61
	v_and_b32_e32 v62, 0xffff0000, v62
	v_fmac_f32_e32 v238, v236, v236
	v_lshlrev_b32_e32 v237, 16, v63
	v_fmac_f32_e32 v238, v62, v62
	v_and_b32_e32 v63, 0xffff0000, v63
	v_fmac_f32_e32 v238, v237, v237
	v_fmac_f32_e32 v238, v63, v63
	ds_bpermute_b32 v239, v204, v238
	s_waitcnt lgkmcnt(0)
	v_add_f32_e32 v238, v238, v239
	ds_bpermute_b32 v239, v205, v238
	s_waitcnt lgkmcnt(0)
	v_add_f32_e32 v238, v238, v239
	ds_bpermute_b32 v239, v214, v238
	s_waitcnt lgkmcnt(0)
	v_add_f32_e32 v238, v238, v239
	ds_bpermute_b32 v239, v215, v238
	s_waitcnt lgkmcnt(0)
	v_add_f32_e32 v238, v238, v239
	v_fmamk_f32 v238, v238, 0x3c000000, v208
	v_mul_f32_e32 v239, 0x4f800000, v238
	v_cmp_gt_f32_e32 vcc, s33, v238
	s_nop 1
	v_cndmask_b32_e32 v238, v238, v239, vcc
	v_sqrt_f32_e32 v239, v238
	s_nop 0
	v_add_u32_e32 v240, -1, v239
	v_add_u32_e32 v241, 1, v239
	v_fma_f32 v242, -v240, v239, v238
	v_fma_f32 v243, -v241, v239, v238
	v_cmp_ge_f32_e64 s[0:1], 0, v242
	s_nop 1
	v_cndmask_b32_e64 v239, v239, v240, s[0:1]
	v_cmp_lt_f32_e64 s[0:1], 0, v243
	s_nop 1
	v_cndmask_b32_e64 v239, v239, v241, s[0:1]
	v_mul_f32_e32 v240, 0x37800000, v239
	v_cndmask_b32_e32 v239, v239, v240, vcc
	v_cmp_class_f32_e32 vcc, v238, v209
	s_nop 1
	v_cndmask_b32_e32 v238, v239, v238, vcc
	v_div_scale_f32 v239, s[0:1], v238, v238, 1.0
	v_rcp_f32_e32 v241, v239
	v_div_scale_f32 v240, vcc, 1.0, v238, 1.0
	v_fma_f32 v242, -v239, v241, 1.0
	v_fmac_f32_e32 v241, v242, v241
	v_mul_f32_e32 v242, v240, v241
	v_fma_f32 v243, -v239, v242, v240
	v_fmac_f32_e32 v242, v243, v241
	v_fma_f32 v239, -v239, v242, v240
	v_div_fmas_f32 v239, v239, v241, v242
	v_div_fixup_f32 v238, v239, v238, 1.0
	v_mul_f32_e32 v217, v217, v238
	v_mul_f32_e32 v60, v217, v60
	v_mul_f32_e32 v61, v217, v61
	v_mul_f32_e32 v62, v217, v62
	v_mul_f32_e32 v63, v217, v63
	v_mul_f32_e32 v234, v217, v234
	v_mul_f32_e32 v235, v217, v235
	v_mul_f32_e32 v236, v217, v236
	v_mul_f32_e32 v237, v217, v237
	v_mul_f32_e32 v60, v219, v60
	v_mul_f32_e32 v61, v221, v61
	v_mul_f32_e32 v62, v223, v62
	v_mul_f32_e32 v63, v225, v63
	v_mul_f32_e32 v244, v218, v234
	v_mul_f32_e32 v245, v220, v235
	v_mul_f32_e32 v246, v222, v236
	v_mul_f32_e32 v247, v224, v237
	v_cvt_pk_bf16_f32 v60, v244, v60
	v_cvt_pk_bf16_f32 v61, v245, v61
	v_cvt_pk_bf16_f32 v62, v246, v62
	v_cvt_pk_bf16_f32 v63, v247, v63
	v_add_u32_e32 v2, 0x200, v216
	v_ashrrev_i32_e32 v3, 31, v2
	v_lshl_add_u64 v[14:15], v[2:3], 1, v[0:1]
	global_store_dwordx4 v[14:15], v[60:63], off
	s_waitcnt vmcnt(19)
	v_mov_b32_e32 v217, v211
	v_lshlrev_b32_e32 v234, 16, v64
	v_and_b32_e32 v64, 0xffff0000, v64
	v_mul_f32_e32 v238, v64, v64
	v_lshlrev_b32_e32 v235, 16, v65
	v_fmac_f32_e32 v238, v234, v234
	v_and_b32_e32 v65, 0xffff0000, v65
	v_fmac_f32_e32 v238, v235, v235
	v_lshlrev_b32_e32 v236, 16, v66
	v_fmac_f32_e32 v238, v65, v65
	v_and_b32_e32 v66, 0xffff0000, v66
	v_fmac_f32_e32 v238, v236, v236
	v_lshlrev_b32_e32 v237, 16, v67
	v_fmac_f32_e32 v238, v66, v66
	v_and_b32_e32 v67, 0xffff0000, v67
	v_fmac_f32_e32 v238, v237, v237
	v_fmac_f32_e32 v238, v67, v67
	ds_bpermute_b32 v239, v204, v238
	s_waitcnt lgkmcnt(0)
	v_add_f32_e32 v238, v238, v239
	ds_bpermute_b32 v239, v205, v238
	s_waitcnt lgkmcnt(0)
; __device__ __forceinline__ unsigned pk2(float lo, float hi) { return pg8::cvt_pk_bf16(lo, hi); }
; __device__ __forceinline__ void idx_unit(bf16* QB, float* SC, int* SEL, const float* qg, const float* kg, int b, int tp, LAS unsigned char* wl, int lane, bool do_norm) {
;     ...
;             const int col = (p < 4) ? (CQ + (4 * p + lg) * 128) : (CK + lg * 128);
;             bf16* ptr = QB + (row + a) * NBP + col + 8 * li;
;             const u32x4 w = *(const u32x4*)ptr;
;             float v[8] = {bflo(w.x), bfhi(w.x), bflo(w.y), bfhi(w.y), bflo(w.z), bfhi(w.z), bflo(w.w), bfhi(w.w)};
;             float s = 0.f;
; #pragma unroll
;             for (int e = 0; e < 8; ++e) s += v[e] * v[e];
;             s += __shfl_xor(s, 1); s += __shfl_xor(s, 2); s += __shfl_xor(s, 4); s += __shfl_xor(s, 8);
;             const float rstd = (1.0f / sqrtf(s * (1.f / 128.f) + RMS_EPS)) * ((p < 4) ? C2 : 1.f);
;             const float* gp = ((p < 4) ? qg : kg) + 8 * li;
;             const f32x4 g0 = *(const f32x4*)gp, g1 = *(const f32x4*)(gp + 4);
;             u32x4 o; o.x = pk2(v[0] * rstd * g0.x, v[1] * rstd * g0.y); o.y = pk2(v[2] * rstd * g0.z, v[3] * rstd * g0.w);
;             o.z = pk2(v[4] * rstd * g1.x, v[5] * rstd * g1.y); o.w = pk2(v[6] * rstd * g1.z, v[7] * rstd * g1.w);
;             *(u32x4*)ptr = o;
	v_add_f32_e32 v238, v238, v239
	ds_bpermute_b32 v239, v214, v238
	s_waitcnt lgkmcnt(0)
	v_add_f32_e32 v238, v238, v239
	ds_bpermute_b32 v239, v215, v238
	s_waitcnt lgkmcnt(0)
	v_add_f32_e32 v238, v238, v239
	v_fmamk_f32 v238, v238, 0x3c000000, v208
	v_mul_f32_e32 v239, 0x4f800000, v238
	v_cmp_gt_f32_e32 vcc, s33, v238
	s_nop 1
	v_cndmask_b32_e32 v238, v238, v239, vcc
	v_sqrt_f32_e32 v239, v238
	s_nop 0
	v_add_u32_e32 v240, -1, v239
	v_add_u32_e32 v241, 1, v239
	v_fma_f32 v242, -v240, v239, v238
	v_fma_f32 v243, -v241, v239, v238
	v_cmp_ge_f32_e64 s[0:1], 0, v242
	s_nop 1
	v_cndmask_b32_e64 v239, v239, v240, s[0:1]
	v_cmp_lt_f32_e64 s[0:1], 0, v243
	s_nop 1
	v_cndmask_b32_e64 v239, v239, v241, s[0:1]
	v_mul_f32_e32 v240, 0x37800000, v239
	v_cndmask_b32_e32 v239, v239, v240, vcc
	v_cmp_class_f32_e32 vcc, v238, v209
	s_nop 1
	v_cndmask_b32_e32 v238, v239, v238, vcc
	v_div_scale_f32 v239, s[0:1], v238, v238, 1.0
	v_rcp_f32_e32 v241, v239
	v_div_scale_f32 v240, vcc, 1.0, v238, 1.0
	v_fma_f32 v242, -v239, v241, 1.0
	v_fmac_f32_e32 v241, v242, v241
	v_mul_f32_e32 v242, v240, v241
	v_fma_f32 v243, -v239, v242, v240
	v_fmac_f32_e32 v242, v243, v241
	v_fma_f32 v239, -v239, v242, v240
	v_div_fmas_f32 v239, v239, v241, v242
	v_div_fixup_f32 v238, v239, v238, 1.0
	v_mul_f32_e32 v217, v217, v238
	v_mul_f32_e32 v64, v217, v64
	v_mul_f32_e32 v65, v217, v65
	v_mul_f32_e32 v66, v217, v66
	v_mul_f32_e32 v67, v217, v67
	v_mul_f32_e32 v234, v217, v234
	v_mul_f32_e32 v235, v217, v235
	v_mul_f32_e32 v236, v217, v236
	v_mul_f32_e32 v237, v217, v237
	v_mul_f32_e32 v64, v219, v64
	v_mul_f32_e32 v65, v221, v65
	v_mul_f32_e32 v66, v223, v66
	v_mul_f32_e32 v67, v225, v67
	v_mul_f32_e32 v244, v218, v234
	v_mul_f32_e32 v245, v220, v235
	v_mul_f32_e32 v246, v222, v236
	v_mul_f32_e32 v247, v224, v237
	v_cvt_pk_bf16_f32 v64, v244, v64
	v_cvt_pk_bf16_f32 v65, v245, v65
	v_cvt_pk_bf16_f32 v66, v246, v66
	v_cvt_pk_bf16_f32 v67, v247, v67
	v_add_u32_e32 v2, 0x400, v216
	v_ashrrev_i32_e32 v3, 31, v2
	v_lshl_add_u64 v[14:15], v[2:3], 1, v[0:1]
	global_store_dwordx4 v[14:15], v[64:67], off
	s_waitcnt vmcnt(19)
	v_mov_b32_e32 v217, v211
	v_lshlrev_b32_e32 v234, 16, v68
	v_and_b32_e32 v68, 0xffff0000, v68
	v_mul_f32_e32 v238, v68, v68
	v_lshlrev_b32_e32 v235, 16, v69
	v_fmac_f32_e32 v238, v234, v234
	v_and_b32_e32 v69, 0xffff0000, v69
	v_fmac_f32_e32 v238, v235, v235
	v_lshlrev_b32_e32 v236, 16, v70
	v_fmac_f32_e32 v238, v69, v69
	v_and_b32_e32 v70, 0xffff0000, v70
	v_fmac_f32_e32 v238, v236, v236
	v_lshlrev_b32_e32 v237, 16, v71
	v_fmac_f32_e32 v238, v70, v70
	v_and_b32_e32 v71, 0xffff0000, v71
	v_fmac_f32_e32 v238, v237, v237
	v_fmac_f32_e32 v238, v71, v71
	ds_bpermute_b32 v239, v204, v238
	s_waitcnt lgkmcnt(0)
	v_add_f32_e32 v238, v238, v239
	ds_bpermute_b32 v239, v205, v238
	s_waitcnt lgkmcnt(0)
	v_add_f32_e32 v238, v238, v239
	ds_bpermute_b32 v239, v214, v238
	s_waitcnt lgkmcnt(0)
	v_add_f32_e32 v238, v238, v239
	ds_bpermute_b32 v239, v215, v238
	s_waitcnt lgkmcnt(0)
	v_add_f32_e32 v238, v238, v239
	v_fmamk_f32 v238, v238, 0x3c000000, v208
	v_mul_f32_e32 v239, 0x4f800000, v238
	v_cmp_gt_f32_e32 vcc, s33, v238
	s_nop 1
	v_cndmask_b32_e32 v238, v238, v239, vcc
	v_sqrt_f32_e32 v239, v238
	s_nop 0
	v_add_u32_e32 v240, -1, v239
	v_add_u32_e32 v241, 1, v239
	v_fma_f32 v242, -v240, v239, v238
	v_fma_f32 v243, -v241, v239, v238
	v_cmp_ge_f32_e64 s[0:1], 0, v242
	s_nop 1
	v_cndmask_b32_e64 v239, v239, v240, s[0:1]
	v_cmp_lt_f32_e64 s[0:1], 0, v243
	s_nop 1
	v_cndmask_b32_e64 v239, v239, v241, s[0:1]
	v_mul_f32_e32 v240, 0x37800000, v239
	v_cndmask_b32_e32 v239, v239, v240, vcc
	v_cmp_class_f32_e32 vcc, v238, v209
	s_nop 1
	v_cndmask_b32_e32 v238, v239, v238, vcc
	v_div_scale_f32 v239, s[0:1], v238, v238, 1.0
	v_rcp_f32_e32 v241, v239
	v_div_scale_f32 v240, vcc, 1.0, v238, 1.0
	v_fma_f32 v242, -v239, v241, 1.0
	v_fmac_f32_e32 v241, v242, v241
	v_mul_f32_e32 v242, v240, v241
	v_fma_f32 v243, -v239, v242, v240
	v_fmac_f32_e32 v242, v243, v241
	v_fma_f32 v239, -v239, v242, v240
	v_div_fmas_f32 v239, v239, v241, v242
	v_div_fixup_f32 v238, v239, v238, 1.0
	v_mul_f32_e32 v217, v217, v238
	v_mul_f32_e32 v68, v217, v68
	v_mul_f32_e32 v69, v217, v69
	v_mul_f32_e32 v70, v217, v70
	v_mul_f32_e32 v71, v217, v71
	v_mul_f32_e32 v234, v217, v234
	v_mul_f32_e32 v235, v217, v235
	v_mul_f32_e32 v236, v217, v236
	v_mul_f32_e32 v237, v217, v237
	v_mul_f32_e32 v68, v219, v68
	v_mul_f32_e32 v69, v221, v69
	v_mul_f32_e32 v70, v223, v70
	v_mul_f32_e32 v71, v225, v71
	v_mul_f32_e32 v244, v218, v234
	v_mul_f32_e32 v245, v220, v235
	v_mul_f32_e32 v246, v222, v236
	v_mul_f32_e32 v247, v224, v237
	v_cvt_pk_bf16_f32 v68, v244, v68
	v_cvt_pk_bf16_f32 v69, v245, v69
	v_cvt_pk_bf16_f32 v70, v246, v70
	v_cvt_pk_bf16_f32 v71, v247, v71
	v_add_u32_e32 v2, 0x600, v216
	v_ashrrev_i32_e32 v3, 31, v2
	v_lshl_add_u64 v[14:15], v[2:3], 1, v[0:1]
	global_store_dwordx4 v[14:15], v[68:71], off
	s_waitcnt vmcnt(19)
	v_mov_b32_e32 v217, 1.0
	v_lshlrev_b32_e32 v234, 16, v72
	v_and_b32_e32 v72, 0xffff0000, v72
	v_mul_f32_e32 v238, v72, v72
	v_lshlrev_b32_e32 v235, 16, v73
	v_fmac_f32_e32 v238, v234, v234
	v_and_b32_e32 v73, 0xffff0000, v73
	v_fmac_f32_e32 v238, v235, v235
	v_lshlrev_b32_e32 v236, 16, v74
	v_fmac_f32_e32 v238, v73, v73
	v_and_b32_e32 v74, 0xffff0000, v74
	v_fmac_f32_e32 v238, v236, v236
	v_lshlrev_b32_e32 v237, 16, v75
	v_fmac_f32_e32 v238, v74, v74
	v_and_b32_e32 v75, 0xffff0000, v75
	v_fmac_f32_e32 v238, v237, v237
	v_fmac_f32_e32 v238, v75, v75
	ds_bpermute_b32 v239, v204, v238
	s_waitcnt lgkmcnt(0)
	v_add_f32_e32 v238, v238, v239
	ds_bpermute_b32 v239, v205, v238
	s_waitcnt lgkmcnt(0)
; __device__ __forceinline__ unsigned pk2(float lo, float hi) { return pg8::cvt_pk_bf16(lo, hi); }
; __device__ __forceinline__ void idx_unit(bf16* QB, float* SC, int* SEL, const float* qg, const float* kg, int b, int tp, LAS unsigned char* wl, int lane, bool do_norm) {
;     ...
;             const int col = (p < 4) ? (CQ + (4 * p + lg) * 128) : (CK + lg * 128);
;             bf16* ptr = QB + (row + a) * NBP + col + 8 * li;
;             const u32x4 w = *(const u32x4*)ptr;
;             float v[8] = {bflo(w.x), bfhi(w.x), bflo(w.y), bfhi(w.y), bflo(w.z), bfhi(w.z), bflo(w.w), bfhi(w.w)};
;             float s = 0.f;
; #pragma unroll
;             for (int e = 0; e < 8; ++e) s += v[e] * v[e];
;             s += __shfl_xor(s, 1); s += __shfl_xor(s, 2); s += __shfl_xor(s, 4); s += __shfl_xor(s, 8);
;             const float rstd = (1.0f / sqrtf(s * (1.f / 128.f) + RMS_EPS)) * ((p < 4) ? C2 : 1.f);
;             const float* gp = ((p < 4) ? qg : kg) + 8 * li;
;             const f32x4 g0 = *(const f32x4*)gp, g1 = *(const f32x4*)(gp + 4);
;             u32x4 o; o.x = pk2(v[0] * rstd * g0.x, v[1] * rstd * g0.y); o.y = pk2(v[2] * rstd * g0.z, v[3] * rstd * g0.w);
;             o.z = pk2(v[4] * rstd * g1.x, v[5] * rstd * g1.y); o.w = pk2(v[6] * rstd * g1.z, v[7] * rstd * g1.w);
;             *(u32x4*)ptr = o;
	v_add_f32_e32 v238, v238, v239
	ds_bpermute_b32 v239, v214, v238
	s_waitcnt lgkmcnt(0)
	v_add_f32_e32 v238, v238, v239
	ds_bpermute_b32 v239, v215, v238
	s_waitcnt lgkmcnt(0)
	v_add_f32_e32 v238, v238, v239
	v_fmamk_f32 v238, v238, 0x3c000000, v208
	v_mul_f32_e32 v239, 0x4f800000, v238
	v_cmp_gt_f32_e32 vcc, s33, v238
	s_nop 1
	v_cndmask_b32_e32 v238, v238, v239, vcc
	v_sqrt_f32_e32 v239, v238
	s_nop 0
	v_add_u32_e32 v240, -1, v239
	v_add_u32_e32 v241, 1, v239
	v_fma_f32 v242, -v240, v239, v238
	v_fma_f32 v243, -v241, v239, v238
	v_cmp_ge_f32_e64 s[0:1], 0, v242
	s_nop 1
	v_cndmask_b32_e64 v239, v239, v240, s[0:1]
	v_cmp_lt_f32_e64 s[0:1], 0, v243
	s_nop 1
	v_cndmask_b32_e64 v239, v239, v241, s[0:1]
	v_mul_f32_e32 v240, 0x37800000, v239
	v_cndmask_b32_e32 v239, v239, v240, vcc
	v_cmp_class_f32_e32 vcc, v238, v209
	s_nop 1
	v_cndmask_b32_e32 v238, v239, v238, vcc
	v_div_scale_f32 v239, s[0:1], v238, v238, 1.0
	v_rcp_f32_e32 v241, v239
	v_div_scale_f32 v240, vcc, 1.0, v238, 1.0
	v_fma_f32 v242, -v239, v241, 1.0
	v_fmac_f32_e32 v241, v242, v241
	v_mul_f32_e32 v242, v240, v241
	v_fma_f32 v243, -v239, v242, v240
	v_fmac_f32_e32 v242, v243, v241
	v_fma_f32 v239, -v239, v242, v240
	v_div_fmas_f32 v239, v239, v241, v242
	v_div_fixup_f32 v238, v239, v238, 1.0
	v_mul_f32_e32 v217, v217, v238
	v_mul_f32_e32 v72, v217, v72
	v_mul_f32_e32 v73, v217, v73
	v_mul_f32_e32 v74, v217, v74
	v_mul_f32_e32 v75, v217, v75
	v_mul_f32_e32 v234, v217, v234
	v_mul_f32_e32 v235, v217, v235
	v_mul_f32_e32 v236, v217, v236
	v_mul_f32_e32 v237, v217, v237
	v_mul_f32_e32 v72, v227, v72
	v_mul_f32_e32 v73, v229, v73
	v_mul_f32_e32 v74, v231, v74
	v_mul_f32_e32 v75, v233, v75
	v_mul_f32_e32 v244, v226, v234
	v_mul_f32_e32 v245, v228, v235
	v_mul_f32_e32 v246, v230, v236
	v_mul_f32_e32 v247, v232, v237
	v_cvt_pk_bf16_f32 v72, v244, v72
	v_cvt_pk_bf16_f32 v73, v245, v73
	v_cvt_pk_bf16_f32 v74, v246, v74
	v_cvt_pk_bf16_f32 v75, v247, v75
	v_add_u32_e32 v2, 0x800, v216
	v_ashrrev_i32_e32 v3, 31, v2
	v_lshl_add_u64 v[14:15], v[2:3], 1, v[0:1]
	global_store_dwordx4 v[14:15], v[72:75], off
	s_add_u32 s0, s2, 3
	s_addc_u32 s1, s79, 0
	s_mul_i32 s4, s1, 0x2200
	v_mad_u64_u32 v[0:1], s[0:1], s0, v212, v[118:119]
	v_add_u32_e32 v1, s4, v1
	s_waitcnt vmcnt(19)
	v_mov_b32_e32 v217, v211
	v_lshlrev_b32_e32 v234, 16, v76
	v_and_b32_e32 v76, 0xffff0000, v76
	v_mul_f32_e32 v238, v76, v76
	v_lshlrev_b32_e32 v235, 16, v77
	v_fmac_f32_e32 v238, v234, v234
	v_and_b32_e32 v77, 0xffff0000, v77
	v_fmac_f32_e32 v238, v235, v235
	v_lshlrev_b32_e32 v236, 16, v78
	v_fmac_f32_e32 v238, v77, v77
	v_and_b32_e32 v78, 0xffff0000, v78
	v_fmac_f32_e32 v238, v236, v236
	v_lshlrev_b32_e32 v237, 16, v79
	v_fmac_f32_e32 v238, v78, v78
	v_and_b32_e32 v79, 0xffff0000, v79
	v_fmac_f32_e32 v238, v237, v237
	v_fmac_f32_e32 v238, v79, v79
	ds_bpermute_b32 v239, v204, v238
	s_waitcnt lgkmcnt(0)
	v_add_f32_e32 v238, v238, v239
	ds_bpermute_b32 v239, v205, v238
	s_waitcnt lgkmcnt(0)
	v_add_f32_e32 v238, v238, v239
	ds_bpermute_b32 v239, v214, v238
	s_waitcnt lgkmcnt(0)
	v_add_f32_e32 v238, v238, v239
	ds_bpermute_b32 v239, v215, v238
	s_waitcnt lgkmcnt(0)
	v_add_f32_e32 v238, v238, v239
	v_fmamk_f32 v238, v238, 0x3c000000, v208
	v_mul_f32_e32 v239, 0x4f800000, v238
	v_cmp_gt_f32_e32 vcc, s33, v238
	s_nop 1
	v_cndmask_b32_e32 v238, v238, v239, vcc
	v_sqrt_f32_e32 v239, v238
	s_nop 0
	v_add_u32_e32 v240, -1, v239
	v_add_u32_e32 v241, 1, v239
	v_fma_f32 v242, -v240, v239, v238
	v_fma_f32 v243, -v241, v239, v238
	v_cmp_ge_f32_e64 s[0:1], 0, v242
	s_nop 1
	v_cndmask_b32_e64 v239, v239, v240, s[0:1]
	v_cmp_lt_f32_e64 s[0:1], 0, v243
	s_nop 1
	v_cndmask_b32_e64 v239, v239, v241, s[0:1]
	v_mul_f32_e32 v240, 0x37800000, v239
	v_cndmask_b32_e32 v239, v239, v240, vcc
	v_cmp_class_f32_e32 vcc, v238, v209
	s_nop 1
	v_cndmask_b32_e32 v238, v239, v238, vcc
	v_div_scale_f32 v239, s[0:1], v238, v238, 1.0
	v_rcp_f32_e32 v241, v239
	v_div_scale_f32 v240, vcc, 1.0, v238, 1.0
	v_fma_f32 v242, -v239, v241, 1.0
	v_fmac_f32_e32 v241, v242, v241
	v_mul_f32_e32 v242, v240, v241
	v_fma_f32 v243, -v239, v242, v240
	v_fmac_f32_e32 v242, v243, v241
	v_fma_f32 v239, -v239, v242, v240
	v_div_fmas_f32 v239, v239, v241, v242
	v_div_fixup_f32 v238, v239, v238, 1.0
	v_mul_f32_e32 v217, v217, v238
	v_mul_f32_e32 v76, v217, v76
	v_mul_f32_e32 v77, v217, v77
	v_mul_f32_e32 v78, v217, v78
	v_mul_f32_e32 v79, v217, v79
	v_mul_f32_e32 v234, v217, v234
	v_mul_f32_e32 v235, v217, v235
	v_mul_f32_e32 v236, v217, v236
	v_mul_f32_e32 v237, v217, v237
	v_mul_f32_e32 v76, v219, v76
	v_mul_f32_e32 v77, v221, v77
	v_mul_f32_e32 v78, v223, v78
	v_mul_f32_e32 v79, v225, v79
	v_mul_f32_e32 v244, v218, v234
	v_mul_f32_e32 v245, v220, v235
	v_mul_f32_e32 v246, v222, v236
	v_mul_f32_e32 v247, v224, v237
	v_cvt_pk_bf16_f32 v76, v244, v76
	v_cvt_pk_bf16_f32 v77, v245, v77
	v_cvt_pk_bf16_f32 v78, v246, v78
	v_cvt_pk_bf16_f32 v79, v247, v79
	v_mov_b32_e32 v2, v216
	v_ashrrev_i32_e32 v3, 31, v2
	v_lshl_add_u64 v[14:15], v[2:3], 1, v[0:1]
	global_store_dwordx4 v[14:15], v[76:79], off
	s_waitcnt vmcnt(19)
	v_mov_b32_e32 v217, v211
	v_lshlrev_b32_e32 v234, 16, v80
	v_and_b32_e32 v80, 0xffff0000, v80
	v_mul_f32_e32 v238, v80, v80
	v_lshlrev_b32_e32 v235, 16, v81
	v_fmac_f32_e32 v238, v234, v234
	v_and_b32_e32 v81, 0xffff0000, v81
	v_fmac_f32_e32 v238, v235, v235
	v_lshlrev_b32_e32 v236, 16, v82
	v_fmac_f32_e32 v238, v81, v81
	v_and_b32_e32 v82, 0xffff0000, v82
	v_fmac_f32_e32 v238, v236, v236
	v_lshlrev_b32_e32 v237, 16, v83
	v_fmac_f32_e32 v238, v82, v82
	v_and_b32_e32 v83, 0xffff0000, v83
	v_fmac_f32_e32 v238, v237, v237
	v_fmac_f32_e32 v238, v83, v83
	ds_bpermute_b32 v239, v204, v238
	s_waitcnt lgkmcnt(0)
; __device__ __forceinline__ unsigned pk2(float lo, float hi) { return pg8::cvt_pk_bf16(lo, hi); }
; __device__ __forceinline__ void idx_unit(bf16* QB, float* SC, int* SEL, const float* qg, const float* kg, int b, int tp, LAS unsigned char* wl, int lane, bool do_norm) {
;     ...
;             const int col = (p < 4) ? (CQ + (4 * p + lg) * 128) : (CK + lg * 128);
;             bf16* ptr = QB + (row + a) * NBP + col + 8 * li;
;             const u32x4 w = *(const u32x4*)ptr;
;             float v[8] = {bflo(w.x), bfhi(w.x), bflo(w.y), bfhi(w.y), bflo(w.z), bfhi(w.z), bflo(w.w), bfhi(w.w)};
;             float s = 0.f;
; #pragma unroll
;             for (int e = 0; e < 8; ++e) s += v[e] * v[e];
;             s += __shfl_xor(s, 1); s += __shfl_xor(s, 2); s += __shfl_xor(s, 4); s += __shfl_xor(s, 8);
;             const float rstd = (1.0f / sqrtf(s * (1.f / 128.f) + RMS_EPS)) * ((p < 4) ? C2 : 1.f);
;             const float* gp = ((p < 4) ? qg : kg) + 8 * li;
;             const f32x4 g0 = *(const f32x4*)gp, g1 = *(const f32x4*)(gp + 4);
;             u32x4 o; o.x = pk2(v[0] * rstd * g0.x, v[1] * rstd * g0.y); o.y = pk2(v[2] * rstd * g0.z, v[3] * rstd * g0.w);
;             o.z = pk2(v[4] * rstd * g1.x, v[5] * rstd * g1.y); o.w = pk2(v[6] * rstd * g1.z, v[7] * rstd * g1.w);
;             *(u32x4*)ptr = o;
	v_add_f32_e32 v238, v238, v239
	ds_bpermute_b32 v239, v205, v238
	s_waitcnt lgkmcnt(0)
	v_add_f32_e32 v238, v238, v239
	ds_bpermute_b32 v239, v214, v238
	s_waitcnt lgkmcnt(0)
	v_add_f32_e32 v238, v238, v239
	ds_bpermute_b32 v239, v215, v238
	s_waitcnt lgkmcnt(0)
	v_add_f32_e32 v238, v238, v239
	v_fmamk_f32 v238, v238, 0x3c000000, v208
	v_mul_f32_e32 v239, 0x4f800000, v238
	v_cmp_gt_f32_e32 vcc, s33, v238
	s_nop 1
	v_cndmask_b32_e32 v238, v238, v239, vcc
	v_sqrt_f32_e32 v239, v238
	s_nop 0
	v_add_u32_e32 v240, -1, v239
	v_add_u32_e32 v241, 1, v239
	v_fma_f32 v242, -v240, v239, v238
	v_fma_f32 v243, -v241, v239, v238
	v_cmp_ge_f32_e64 s[0:1], 0, v242
	s_nop 1
	v_cndmask_b32_e64 v239, v239, v240, s[0:1]
	v_cmp_lt_f32_e64 s[0:1], 0, v243
	s_nop 1
	v_cndmask_b32_e64 v239, v239, v241, s[0:1]
	v_mul_f32_e32 v240, 0x37800000, v239
	v_cndmask_b32_e32 v239, v239, v240, vcc
	v_cmp_class_f32_e32 vcc, v238, v209
	s_nop 1
	v_cndmask_b32_e32 v238, v239, v238, vcc
	v_div_scale_f32 v239, s[0:1], v238, v238, 1.0
	v_rcp_f32_e32 v241, v239
	v_div_scale_f32 v240, vcc, 1.0, v238, 1.0
	v_fma_f32 v242, -v239, v241, 1.0
	v_fmac_f32_e32 v241, v242, v241
	v_mul_f32_e32 v242, v240, v241
	v_fma_f32 v243, -v239, v242, v240
	v_fmac_f32_e32 v242, v243, v241
	v_fma_f32 v239, -v239, v242, v240
	v_div_fmas_f32 v239, v239, v241, v242
	v_div_fixup_f32 v238, v239, v238, 1.0
	v_mul_f32_e32 v217, v217, v238
	v_mul_f32_e32 v80, v217, v80
	v_mul_f32_e32 v81, v217, v81
	v_mul_f32_e32 v82, v217, v82
	v_mul_f32_e32 v83, v217, v83
	v_mul_f32_e32 v234, v217, v234
	v_mul_f32_e32 v235, v217, v235
	v_mul_f32_e32 v236, v217, v236
	v_mul_f32_e32 v237, v217, v237
	v_mul_f32_e32 v80, v219, v80
	v_mul_f32_e32 v81, v221, v81
	v_mul_f32_e32 v82, v223, v82
	v_mul_f32_e32 v83, v225, v83
	v_mul_f32_e32 v244, v218, v234
	v_mul_f32_e32 v245, v220, v235
	v_mul_f32_e32 v246, v222, v236
	v_mul_f32_e32 v247, v224, v237
	v_cvt_pk_bf16_f32 v80, v244, v80
	v_cvt_pk_bf16_f32 v81, v245, v81
	v_cvt_pk_bf16_f32 v82, v246, v82
	v_cvt_pk_bf16_f32 v83, v247, v83
	v_add_u32_e32 v2, 0x200, v216
	v_ashrrev_i32_e32 v3, 31, v2
	v_lshl_add_u64 v[14:15], v[2:3], 1, v[0:1]
	global_store_dwordx4 v[14:15], v[80:83], off
	s_waitcnt vmcnt(19)
	v_mov_b32_e32 v217, v211
	v_lshlrev_b32_e32 v234, 16, v84
	v_and_b32_e32 v84, 0xffff0000, v84
	v_mul_f32_e32 v238, v84, v84
	v_lshlrev_b32_e32 v235, 16, v85
	v_fmac_f32_e32 v238, v234, v234
	v_and_b32_e32 v85, 0xffff0000, v85
	v_fmac_f32_e32 v238, v235, v235
	v_lshlrev_b32_e32 v236, 16, v86
	v_fmac_f32_e32 v238, v85, v85
	v_and_b32_e32 v86, 0xffff0000, v86
	v_fmac_f32_e32 v238, v236, v236
	v_lshlrev_b32_e32 v237, 16, v87
	v_fmac_f32_e32 v238, v86, v86
	v_and_b32_e32 v87, 0xffff0000, v87
	v_fmac_f32_e32 v238, v237, v237
	v_fmac_f32_e32 v238, v87, v87
	ds_bpermute_b32 v239, v204, v238
	s_waitcnt lgkmcnt(0)
	v_add_f32_e32 v238, v238, v239
	ds_bpermute_b32 v239, v205, v238
	s_waitcnt lgkmcnt(0)
	v_add_f32_e32 v238, v238, v239
	ds_bpermute_b32 v239, v214, v238
	s_waitcnt lgkmcnt(0)
	v_add_f32_e32 v238, v238, v239
	ds_bpermute_b32 v239, v215, v238
	s_waitcnt lgkmcnt(0)
	v_add_f32_e32 v238, v238, v239
	v_fmamk_f32 v238, v238, 0x3c000000, v208
	v_mul_f32_e32 v239, 0x4f800000, v238
	v_cmp_gt_f32_e32 vcc, s33, v238
	s_nop 1
	v_cndmask_b32_e32 v238, v238, v239, vcc
	v_sqrt_f32_e32 v239, v238
	s_nop 0
	v_add_u32_e32 v240, -1, v239
	v_add_u32_e32 v241, 1, v239
	v_fma_f32 v242, -v240, v239, v238
	v_fma_f32 v243, -v241, v239, v238
	v_cmp_ge_f32_e64 s[0:1], 0, v242
	s_nop 1
	v_cndmask_b32_e64 v239, v239, v240, s[0:1]
	v_cmp_lt_f32_e64 s[0:1], 0, v243
	s_nop 1
	v_cndmask_b32_e64 v239, v239, v241, s[0:1]
	v_mul_f32_e32 v240, 0x37800000, v239
	v_cndmask_b32_e32 v239, v239, v240, vcc
	v_cmp_class_f32_e32 vcc, v238, v209
	s_nop 1
	v_cndmask_b32_e32 v238, v239, v238, vcc
	v_div_scale_f32 v239, s[0:1], v238, v238, 1.0
	v_rcp_f32_e32 v241, v239
	v_div_scale_f32 v240, vcc, 1.0, v238, 1.0
	v_fma_f32 v242, -v239, v241, 1.0
	v_fmac_f32_e32 v241, v242, v241
	v_mul_f32_e32 v242, v240, v241
	v_fma_f32 v243, -v239, v242, v240
	v_fmac_f32_e32 v242, v243, v241
	v_fma_f32 v239, -v239, v242, v240
	v_div_fmas_f32 v239, v239, v241, v242
	v_div_fixup_f32 v238, v239, v238, 1.0
	v_mul_f32_e32 v217, v217, v238
	v_mul_f32_e32 v84, v217, v84
	v_mul_f32_e32 v85, v217, v85
	v_mul_f32_e32 v86, v217, v86
	v_mul_f32_e32 v87, v217, v87
	v_mul_f32_e32 v234, v217, v234
	v_mul_f32_e32 v235, v217, v235
	v_mul_f32_e32 v236, v217, v236
	v_mul_f32_e32 v237, v217, v237
	v_mul_f32_e32 v84, v219, v84
	v_mul_f32_e32 v85, v221, v85
	v_mul_f32_e32 v86, v223, v86
	v_mul_f32_e32 v87, v225, v87
	v_mul_f32_e32 v244, v218, v234
	v_mul_f32_e32 v245, v220, v235
	v_mul_f32_e32 v246, v222, v236
	v_mul_f32_e32 v247, v224, v237
	v_cvt_pk_bf16_f32 v84, v244, v84
	v_cvt_pk_bf16_f32 v85, v245, v85
	v_cvt_pk_bf16_f32 v86, v246, v86
	v_cvt_pk_bf16_f32 v87, v247, v87
	v_add_u32_e32 v2, 0x400, v216
	v_ashrrev_i32_e32 v3, 31, v2
	v_lshl_add_u64 v[14:15], v[2:3], 1, v[0:1]
	global_store_dwordx4 v[14:15], v[84:87], off
	s_waitcnt vmcnt(19)
	v_mov_b32_e32 v217, v211
	v_lshlrev_b32_e32 v234, 16, v88
	v_and_b32_e32 v88, 0xffff0000, v88
	v_mul_f32_e32 v238, v88, v88
	v_lshlrev_b32_e32 v235, 16, v89
	v_fmac_f32_e32 v238, v234, v234
	v_and_b32_e32 v89, 0xffff0000, v89
	v_fmac_f32_e32 v238, v235, v235
	v_lshlrev_b32_e32 v236, 16, v90
	v_fmac_f32_e32 v238, v89, v89
	v_and_b32_e32 v90, 0xffff0000, v90
	v_fmac_f32_e32 v238, v236, v236
	v_lshlrev_b32_e32 v237, 16, v91
	v_fmac_f32_e32 v238, v90, v90
	v_and_b32_e32 v91, 0xffff0000, v91
	v_fmac_f32_e32 v238, v237, v237
	v_fmac_f32_e32 v238, v91, v91
	ds_bpermute_b32 v239, v204, v238
	s_waitcnt lgkmcnt(0)
; __device__ __forceinline__ unsigned pk2(float lo, float hi) { return pg8::cvt_pk_bf16(lo, hi); }
; __device__ __forceinline__ void idx_unit(bf16* QB, float* SC, int* SEL, const float* qg, const float* kg, int b, int tp, LAS unsigned char* wl, int lane, bool do_norm) {
;     ...
;             const int col = (p < 4) ? (CQ + (4 * p + lg) * 128) : (CK + lg * 128);
;             bf16* ptr = QB + (row + a) * NBP + col + 8 * li;
;             const u32x4 w = *(const u32x4*)ptr;
;             float v[8] = {bflo(w.x), bfhi(w.x), bflo(w.y), bfhi(w.y), bflo(w.z), bfhi(w.z), bflo(w.w), bfhi(w.w)};
;             float s = 0.f;
; #pragma unroll
;             for (int e = 0; e < 8; ++e) s += v[e] * v[e];
;             s += __shfl_xor(s, 1); s += __shfl_xor(s, 2); s += __shfl_xor(s, 4); s += __shfl_xor(s, 8);
;             const float rstd = (1.0f / sqrtf(s * (1.f / 128.f) + RMS_EPS)) * ((p < 4) ? C2 : 1.f);
;             const float* gp = ((p < 4) ? qg : kg) + 8 * li;
;             const f32x4 g0 = *(const f32x4*)gp, g1 = *(const f32x4*)(gp + 4);
;             u32x4 o; o.x = pk2(v[0] * rstd * g0.x, v[1] * rstd * g0.y); o.y = pk2(v[2] * rstd * g0.z, v[3] * rstd * g0.w);
;             o.z = pk2(v[4] * rstd * g1.x, v[5] * rstd * g1.y); o.w = pk2(v[6] * rstd * g1.z, v[7] * rstd * g1.w);
;             *(u32x4*)ptr = o;
; __global__ void __launch_bounds__(NWAVES * 64, 2) fwd_megakernel(Args args) {
;     ...
;                 for (int rep = 0; rep < REP_IDX; ++rep) for (int i = 0; i * ngw < NBATCH * per; ++i) { const int u = i * ngw + gw; if (u >= NBATCH * per) break;
;                     const int bb = u / per; int tp = u % per; if (i & 1) tp = per - 1 - tp;
;     ...
;  idx_unit(QKV, SC, SEL, args.in[I_QN] + j * 128, args.in[I_KN] + j * 128, bb, tp, wl, lane, rep == REP_IDX - 1);
;     ...
;  }
	v_add_f32_e32 v238, v238, v239
	ds_bpermute_b32 v239, v205, v238
	s_waitcnt lgkmcnt(0)
	v_add_f32_e32 v238, v238, v239
	ds_bpermute_b32 v239, v214, v238
	s_waitcnt lgkmcnt(0)
	v_add_f32_e32 v238, v238, v239
	ds_bpermute_b32 v239, v215, v238
	s_waitcnt lgkmcnt(0)
	v_add_f32_e32 v238, v238, v239
	v_fmamk_f32 v238, v238, 0x3c000000, v208
	v_mul_f32_e32 v239, 0x4f800000, v238
	v_cmp_gt_f32_e32 vcc, s33, v238
	s_nop 1
	v_cndmask_b32_e32 v238, v238, v239, vcc
	v_sqrt_f32_e32 v239, v238
	s_nop 0
	v_add_u32_e32 v240, -1, v239
	v_add_u32_e32 v241, 1, v239
	v_fma_f32 v242, -v240, v239, v238
	v_fma_f32 v243, -v241, v239, v238
	v_cmp_ge_f32_e64 s[0:1], 0, v242
	s_nop 1
	v_cndmask_b32_e64 v239, v239, v240, s[0:1]
	v_cmp_lt_f32_e64 s[0:1], 0, v243
	s_nop 1
	v_cndmask_b32_e64 v239, v239, v241, s[0:1]
	v_mul_f32_e32 v240, 0x37800000, v239
	v_cndmask_b32_e32 v239, v239, v240, vcc
	v_cmp_class_f32_e32 vcc, v238, v209
	s_nop 1
	v_cndmask_b32_e32 v238, v239, v238, vcc
	v_div_scale_f32 v239, s[0:1], v238, v238, 1.0
	v_rcp_f32_e32 v241, v239
	v_div_scale_f32 v240, vcc, 1.0, v238, 1.0
	v_fma_f32 v242, -v239, v241, 1.0
	v_fmac_f32_e32 v241, v242, v241
	v_mul_f32_e32 v242, v240, v241
	v_fma_f32 v243, -v239, v242, v240
	v_fmac_f32_e32 v242, v243, v241
	v_fma_f32 v239, -v239, v242, v240
	v_div_fmas_f32 v239, v239, v241, v242
	v_div_fixup_f32 v238, v239, v238, 1.0
	v_mul_f32_e32 v217, v217, v238
	v_mul_f32_e32 v88, v217, v88
	v_mul_f32_e32 v89, v217, v89
	v_mul_f32_e32 v90, v217, v90
	v_mul_f32_e32 v91, v217, v91
	v_mul_f32_e32 v234, v217, v234
	v_mul_f32_e32 v235, v217, v235
	v_mul_f32_e32 v236, v217, v236
	v_mul_f32_e32 v237, v217, v237
	v_mul_f32_e32 v88, v219, v88
	v_mul_f32_e32 v89, v221, v89
	v_mul_f32_e32 v90, v223, v90
	v_mul_f32_e32 v91, v225, v91
	v_mul_f32_e32 v244, v218, v234
	v_mul_f32_e32 v245, v220, v235
	v_mul_f32_e32 v246, v222, v236
	v_mul_f32_e32 v247, v224, v237
	v_cvt_pk_bf16_f32 v88, v244, v88
	v_cvt_pk_bf16_f32 v89, v245, v89
	v_cvt_pk_bf16_f32 v90, v246, v90
	v_cvt_pk_bf16_f32 v91, v247, v91
	v_add_u32_e32 v2, 0x600, v216
	v_ashrrev_i32_e32 v3, 31, v2
	v_lshl_add_u64 v[14:15], v[2:3], 1, v[0:1]
	global_store_dwordx4 v[14:15], v[88:91], off
	s_waitcnt vmcnt(19)
	v_mov_b32_e32 v217, 1.0
	v_lshlrev_b32_e32 v234, 16, v92
	v_and_b32_e32 v92, 0xffff0000, v92
	v_mul_f32_e32 v238, v92, v92
	v_lshlrev_b32_e32 v235, 16, v93
	v_fmac_f32_e32 v238, v234, v234
	v_and_b32_e32 v93, 0xffff0000, v93
	v_fmac_f32_e32 v238, v235, v235
	v_lshlrev_b32_e32 v236, 16, v94
	v_fmac_f32_e32 v238, v93, v93
	v_and_b32_e32 v94, 0xffff0000, v94
	v_fmac_f32_e32 v238, v236, v236
	v_lshlrev_b32_e32 v237, 16, v95
	v_fmac_f32_e32 v238, v94, v94
	v_and_b32_e32 v95, 0xffff0000, v95
	v_fmac_f32_e32 v238, v237, v237
	v_fmac_f32_e32 v238, v95, v95
	ds_bpermute_b32 v239, v204, v238
	s_waitcnt lgkmcnt(0)
	v_add_f32_e32 v238, v238, v239
	ds_bpermute_b32 v239, v205, v238
	s_waitcnt lgkmcnt(0)
	v_add_f32_e32 v238, v238, v239
	ds_bpermute_b32 v239, v214, v238
	s_waitcnt lgkmcnt(0)
	v_add_f32_e32 v238, v238, v239
	ds_bpermute_b32 v239, v215, v238
	s_waitcnt lgkmcnt(0)
	v_add_f32_e32 v238, v238, v239
	v_fmamk_f32 v238, v238, 0x3c000000, v208
	v_mul_f32_e32 v239, 0x4f800000, v238
	v_cmp_gt_f32_e32 vcc, s33, v238
	s_nop 1
	v_cndmask_b32_e32 v238, v238, v239, vcc
	v_sqrt_f32_e32 v239, v238
	s_nop 0
	v_add_u32_e32 v240, -1, v239
	v_add_u32_e32 v241, 1, v239
	v_fma_f32 v242, -v240, v239, v238
	v_fma_f32 v243, -v241, v239, v238
	v_cmp_ge_f32_e64 s[0:1], 0, v242
	s_nop 1
	v_cndmask_b32_e64 v239, v239, v240, s[0:1]
	v_cmp_lt_f32_e64 s[0:1], 0, v243
	s_nop 1
	v_cndmask_b32_e64 v239, v239, v241, s[0:1]
	v_mul_f32_e32 v240, 0x37800000, v239
	v_cndmask_b32_e32 v239, v239, v240, vcc
	v_cmp_class_f32_e32 vcc, v238, v209
	s_nop 1
	v_cndmask_b32_e32 v238, v239, v238, vcc
	v_div_scale_f32 v239, s[0:1], v238, v238, 1.0
	v_rcp_f32_e32 v241, v239
	v_div_scale_f32 v240, vcc, 1.0, v238, 1.0
	v_fma_f32 v242, -v239, v241, 1.0
	v_fmac_f32_e32 v241, v242, v241
	v_mul_f32_e32 v242, v240, v241
	v_fma_f32 v243, -v239, v242, v240
	v_fmac_f32_e32 v242, v243, v241
	v_fma_f32 v239, -v239, v242, v240
	v_div_fmas_f32 v239, v239, v241, v242
	v_div_fixup_f32 v238, v239, v238, 1.0
	v_mul_f32_e32 v217, v217, v238
	v_mul_f32_e32 v92, v217, v92
	v_mul_f32_e32 v93, v217, v93
	v_mul_f32_e32 v94, v217, v94
	v_mul_f32_e32 v95, v217, v95
	v_mul_f32_e32 v234, v217, v234
	v_mul_f32_e32 v235, v217, v235
	v_mul_f32_e32 v236, v217, v236
	v_mul_f32_e32 v237, v217, v237
	v_mul_f32_e32 v92, v227, v92
	v_mul_f32_e32 v93, v229, v93
	v_mul_f32_e32 v94, v231, v94
	v_mul_f32_e32 v95, v233, v95
	v_mul_f32_e32 v244, v226, v234
	v_mul_f32_e32 v245, v228, v235
	v_mul_f32_e32 v246, v230, v236
	v_mul_f32_e32 v247, v232, v237
	v_cvt_pk_bf16_f32 v92, v244, v92
	v_cvt_pk_bf16_f32 v93, v245, v93
	v_cvt_pk_bf16_f32 v94, v246, v94
	v_cvt_pk_bf16_f32 v95, v247, v95
	v_add_u32_e32 v2, 0x800, v216
	v_ashrrev_i32_e32 v3, 31, v2
	v_lshl_add_u64 v[14:15], v[2:3], 1, v[0:1]
	global_store_dwordx4 v[14:15], v[92:95], off
	s_mov_b32 s3, 4
	s_add_i32 s11, s11, 1
	s_mul_i32 s2, s11, s84
	s_cmpk_gt_i32 s2, 0xfff
	v_readlane_b32 s78, v253, 53
	s_cselect_b64 s[0:1], -1, 0
	v_readlane_b32 s79, v253, 54
	s_movk_i32 s90, 0x2000
	s_movk_i32 s91, 0x2200
	s_mov_b64 s[96:97], 0x2000
	s_branch .LBB0_229
